# v66 + W2 layer-0 epilogue: all 16 residual loads issued up front with counted vmcnt(15) waits; phase-5 (EpiRes0) epilogue: first 5 row-steps' x loads hoisted
# speedup vs baseline: 1.0147x; 1.0026x over previous
.LBB0_332:
	ds_read_b128 v[142:145], v163
	ds_read_b128 v[146:149], v163 offset:1024
	ds_read_b128 v[166:169], v163 offset:2048
	ds_read_b128 v[170:173], v163 offset:3072
	s_add_u32 s34, s30, 0xfffc0080
	s_addc_u32 s35, s31, -1
	s_cmp_eq_u32 s63, 12
	s_cselect_b32 s37, s27, s35
	s_cselect_b32 s36, s26, s34
	s_cselect_b32 s35, s29, s62
	s_cselect_b32 s34, s28, s61
	v_lshl_add_u64 v[206:207], s[30:31], 0, v[136:137]
	s_add_i32 m0, s43, 0xc000
	ds_read_b128 v[174:177], v164
	ds_read_b128 v[178:181], v164 offset:1024
	ds_read_b128 v[182:185], v164 offset:2048
	ds_read_b128 v[186:189], v164 offset:3072
	ds_read_b128 v[190:193], v164 offset:4096
	ds_read_b128 v[194:197], v164 offset:5120
	ds_read_b128 v[198:201], v164 offset:6144
	ds_read_b128 v[202:205], v164 offset:7168
	global_load_lds_dwordx4 v[206:207], off
	v_lshl_add_u64 v[206:207], s[30:31], 0, v[138:139]
	s_add_i32 m0, s43, 0xe000
	s_nop 0
	global_load_lds_dwordx4 v[206:207], off
	s_waitcnt lgkmcnt(8)
	s_barrier
	s_waitcnt lgkmcnt(0)
	s_setprio 1
	s_waitcnt lgkmcnt(0)
	v_mfma_f32_16x16x32_bf16 v[124:127], v[142:145], v[174:177], v[124:127]
	v_mfma_f32_16x16x32_bf16 v[120:123], v[166:169], v[174:177], v[120:123]
	v_mfma_f32_16x16x32_bf16 v[112:115], v[142:145], v[182:185], v[112:115]
	v_mfma_f32_16x16x32_bf16 v[104:107], v[166:169], v[182:185], v[104:107]
	v_mfma_f32_16x16x32_bf16 v[96:99], v[142:145], v[190:193], v[96:99]
	v_mfma_f32_16x16x32_bf16 v[88:91], v[166:169], v[190:193], v[88:91]
	v_mfma_f32_16x16x32_bf16 v[80:83], v[142:145], v[198:201], v[80:83]
	v_mfma_f32_16x16x32_bf16 v[72:75], v[166:169], v[198:201], v[72:75]
	v_mfma_f32_16x16x32_bf16 v[124:127], v[146:149], v[178:181], v[124:127]
	v_mfma_f32_16x16x32_bf16 v[120:123], v[170:173], v[178:181], v[120:123]
	v_mfma_f32_16x16x32_bf16 v[112:115], v[146:149], v[186:189], v[112:115]
	v_mfma_f32_16x16x32_bf16 v[104:107], v[170:173], v[186:189], v[104:107]
	v_mfma_f32_16x16x32_bf16 v[96:99], v[146:149], v[194:197], v[96:99]
	v_mfma_f32_16x16x32_bf16 v[88:91], v[170:173], v[194:197], v[88:91]
	v_mfma_f32_16x16x32_bf16 v[80:83], v[146:149], v[202:205], v[80:83]
	v_mfma_f32_16x16x32_bf16 v[72:75], v[170:173], v[202:205], v[72:75]
	s_setprio 0
	s_barrier
	s_add_i32 s64, s57, s42
	v_lshl_add_u64 v[222:223], s[34:35], 0, v[130:131]
	s_mov_b32 m0, s64
	ds_read_b128 v[206:209], v165
	ds_read_b128 v[210:213], v165 offset:1024
	ds_read_b128 v[214:217], v165 offset:2048
	ds_read_b128 v[218:221], v165 offset:3072
	global_load_lds_dwordx4 v[222:223], off
	v_lshl_add_u64 v[224:225], s[34:35], 0, v[134:135]
	s_add_i32 m0, s64, 0x2000
	s_nop 0
	global_load_lds_dwordx4 v[224:225], off
	s_barrier
	s_waitcnt lgkmcnt(0)
	s_setprio 1
	s_waitcnt lgkmcnt(0)
	v_mfma_f32_16x16x32_bf16 v[116:119], v[206:209], v[174:177], v[116:119]
	v_mfma_f32_16x16x32_bf16 v[108:111], v[214:217], v[174:177], v[108:111]
	v_mfma_f32_16x16x32_bf16 v[100:103], v[206:209], v[182:185], v[100:103]
	v_mfma_f32_16x16x32_bf16 v[92:95], v[214:217], v[182:185], v[92:95]
	v_mfma_f32_16x16x32_bf16 v[84:87], v[206:209], v[190:193], v[84:87]
	v_mfma_f32_16x16x32_bf16 v[76:79], v[214:217], v[190:193], v[76:79]
	v_mfma_f32_16x16x32_bf16 v[68:71], v[206:209], v[198:201], v[68:71]
	v_mfma_f32_16x16x32_bf16 v[64:67], v[214:217], v[198:201], v[64:67]
	v_mfma_f32_16x16x32_bf16 v[116:119], v[210:213], v[178:181], v[116:119]
	v_mfma_f32_16x16x32_bf16 v[108:111], v[218:221], v[178:181], v[108:111]
	v_mfma_f32_16x16x32_bf16 v[100:103], v[210:213], v[186:189], v[100:103]
	v_mfma_f32_16x16x32_bf16 v[92:95], v[218:221], v[186:189], v[92:95]
	v_mfma_f32_16x16x32_bf16 v[84:87], v[210:213], v[194:197], v[84:87]
	v_mfma_f32_16x16x32_bf16 v[76:79], v[218:221], v[194:197], v[76:79]
	v_mfma_f32_16x16x32_bf16 v[68:71], v[210:213], v[202:205], v[68:71]
	v_mfma_f32_16x16x32_bf16 v[64:67], v[218:221], v[202:205], v[64:67]
	s_setprio 0
	s_mov_b32 m0, s43
	v_lshl_add_u64 v[226:227], s[36:37], 0, v[128:129]
	s_barrier
	ds_read_b128 v[174:177], v164 offset:16384
	ds_read_b128 v[178:181], v164 offset:17408
	ds_read_b128 v[182:185], v164 offset:18432
	ds_read_b128 v[186:189], v164 offset:19456
	ds_read_b128 v[190:193], v164 offset:20480
	ds_read_b128 v[194:197], v164 offset:21504
	ds_read_b128 v[198:201], v164 offset:22528
	ds_read_b128 v[202:205], v164 offset:23552
	global_load_lds_dwordx4 v[226:227], off
	v_lshl_add_u64 v[228:229], s[36:37], 0, v[132:133]
	s_mov_b32 m0, s44
	s_nop 0
	global_load_lds_dwordx4 v[228:229], off
	s_barrier
	s_waitcnt lgkmcnt(0)
	s_setprio 1
	s_waitcnt lgkmcnt(0)
	v_mfma_f32_16x16x32_bf16 v[60:63], v[142:145], v[174:177], v[60:63]
	v_mfma_f32_16x16x32_bf16 v[56:59], v[166:169], v[174:177], v[56:59]
	v_mfma_f32_16x16x32_bf16 v[48:51], v[142:145], v[182:185], v[48:51]
	v_mfma_f32_16x16x32_bf16 v[40:43], v[166:169], v[182:185], v[40:43]
	v_mfma_f32_16x16x32_bf16 v[32:35], v[142:145], v[190:193], v[32:35]
	v_mfma_f32_16x16x32_bf16 v[24:27], v[166:169], v[190:193], v[24:27]
	v_mfma_f32_16x16x32_bf16 v[12:15], v[142:145], v[198:201], v[12:15]
	v_mfma_f32_16x16x32_bf16 v[8:11], v[166:169], v[198:201], v[8:11]
	v_mfma_f32_16x16x32_bf16 v[60:63], v[146:149], v[178:181], v[60:63]
	v_mfma_f32_16x16x32_bf16 v[56:59], v[170:173], v[178:181], v[56:59]
	v_mfma_f32_16x16x32_bf16 v[48:51], v[146:149], v[186:189], v[48:51]
	v_mfma_f32_16x16x32_bf16 v[40:43], v[170:173], v[186:189], v[40:43]
	v_mfma_f32_16x16x32_bf16 v[32:35], v[146:149], v[194:197], v[32:35]
	v_mfma_f32_16x16x32_bf16 v[24:27], v[170:173], v[194:197], v[24:27]
	v_mfma_f32_16x16x32_bf16 v[12:15], v[146:149], v[202:205], v[12:15]
	v_mfma_f32_16x16x32_bf16 v[8:11], v[170:173], v[202:205], v[8:11]
	s_setprio 0
	s_barrier
	s_add_u32 s64, s34, 0x40000
	s_addc_u32 s65, s35, 0
	s_add_i32 s66, s58, s42
	v_lshl_add_u64 v[142:143], s[64:65], 0, v[130:131]
	s_mov_b32 m0, s66
	s_nop 0
	global_load_lds_dwordx4 v[142:143], off
	v_lshl_add_u64 v[142:143], s[64:65], 0, v[134:135]
	s_add_i32 m0, s66, 0x2000
	s_nop 0
	global_load_lds_dwordx4 v[142:143], off
	s_waitcnt vmcnt(6)
	s_barrier
	s_setprio 1
	v_mfma_f32_16x16x32_bf16 v[52:55], v[206:209], v[174:177], v[52:55]
	v_mfma_f32_16x16x32_bf16 v[44:47], v[214:217], v[174:177], v[44:47]
	v_mfma_f32_16x16x32_bf16 v[36:39], v[206:209], v[182:185], v[36:39]
	v_mfma_f32_16x16x32_bf16 v[28:31], v[214:217], v[182:185], v[28:31]
	v_mfma_f32_16x16x32_bf16 v[20:23], v[206:209], v[190:193], v[20:23]
	v_mfma_f32_16x16x32_bf16 v[16:19], v[214:217], v[190:193], v[16:19]
	v_mfma_f32_16x16x32_bf16 v[4:7], v[206:209], v[198:201], v[4:7]
	v_mfma_f32_16x16x32_bf16 v[0:3], v[214:217], v[198:201], v[0:3]
	v_mfma_f32_16x16x32_bf16 v[52:55], v[210:213], v[178:181], v[52:55]
	v_mfma_f32_16x16x32_bf16 v[44:47], v[218:221], v[178:181], v[44:47]
	v_mfma_f32_16x16x32_bf16 v[36:39], v[210:213], v[186:189], v[36:39]
	v_mfma_f32_16x16x32_bf16 v[28:31], v[218:221], v[186:189], v[28:31]
	v_mfma_f32_16x16x32_bf16 v[20:23], v[210:213], v[194:197], v[20:23]
	v_mfma_f32_16x16x32_bf16 v[16:19], v[218:221], v[194:197], v[16:19]
	v_mfma_f32_16x16x32_bf16 v[4:7], v[210:213], v[202:205], v[4:7]
	v_mfma_f32_16x16x32_bf16 v[0:3], v[218:221], v[202:205], v[0:3]
	s_setprio 0
	s_add_i32 s64, 0, 0x18000
	v_add_u32_e32 v170, s64, v151
	s_barrier
	ds_read_b128 v[142:145], v170
	ds_read_b128 v[146:149], v170 offset:1024
	ds_read_b128 v[166:169], v170 offset:2048
	ds_read_b128 v[170:173], v170 offset:3072
	s_add_u32 s36, s36, 0x40000
	s_addc_u32 s37, s37, 0
	s_mov_b32 m0, s45
	v_lshl_add_u64 v[206:207], s[36:37], 0, v[128:129]
	ds_read_b128 v[174:177], v164 offset:32768
	ds_read_b128 v[178:181], v164 offset:33792
	ds_read_b128 v[182:185], v164 offset:34816
	ds_read_b128 v[186:189], v164 offset:35840
	ds_read_b128 v[190:193], v164 offset:36864
	ds_read_b128 v[194:197], v164 offset:37888
	ds_read_b128 v[198:201], v164 offset:38912
	ds_read_b128 v[202:205], v164 offset:39936
	global_load_lds_dwordx4 v[206:207], off
	v_lshl_add_u64 v[206:207], s[36:37], 0, v[132:133]
	s_mov_b32 m0, s46
	s_nop 0
	global_load_lds_dwordx4 v[206:207], off
	s_waitcnt lgkmcnt(8)
	s_barrier
	s_waitcnt lgkmcnt(0)
	s_setprio 1
	s_waitcnt lgkmcnt(0)
	v_mfma_f32_16x16x32_bf16 v[124:127], v[142:145], v[174:177], v[124:127]
	v_mfma_f32_16x16x32_bf16 v[120:123], v[166:169], v[174:177], v[120:123]
	v_mfma_f32_16x16x32_bf16 v[112:115], v[142:145], v[182:185], v[112:115]
	v_mfma_f32_16x16x32_bf16 v[104:107], v[166:169], v[182:185], v[104:107]
	v_mfma_f32_16x16x32_bf16 v[96:99], v[142:145], v[190:193], v[96:99]
	v_mfma_f32_16x16x32_bf16 v[88:91], v[166:169], v[190:193], v[88:91]
	v_mfma_f32_16x16x32_bf16 v[80:83], v[142:145], v[198:201], v[80:83]
	v_mfma_f32_16x16x32_bf16 v[72:75], v[166:169], v[198:201], v[72:75]
	v_mfma_f32_16x16x32_bf16 v[124:127], v[146:149], v[178:181], v[124:127]
	v_mfma_f32_16x16x32_bf16 v[120:123], v[170:173], v[178:181], v[120:123]
	v_mfma_f32_16x16x32_bf16 v[112:115], v[146:149], v[186:189], v[112:115]
	v_mfma_f32_16x16x32_bf16 v[104:107], v[170:173], v[186:189], v[104:107]
	v_mfma_f32_16x16x32_bf16 v[96:99], v[146:149], v[194:197], v[96:99]
	v_mfma_f32_16x16x32_bf16 v[88:91], v[170:173], v[194:197], v[88:91]
	v_mfma_f32_16x16x32_bf16 v[80:83], v[146:149], v[202:205], v[80:83]
	v_mfma_f32_16x16x32_bf16 v[72:75], v[170:173], v[202:205], v[72:75]
	s_setprio 0
	s_barrier
	s_add_i32 s36, 0, 0x1c000
	s_add_i32 s37, s64, s42
	v_add_u32_e32 v218, s36, v151
	v_lshl_add_u64 v[222:223], v[222:223], 0, s[10:11]
	s_mov_b32 m0, s37
	ds_read_b128 v[206:209], v218
	ds_read_b128 v[210:213], v218 offset:1024
	ds_read_b128 v[214:217], v218 offset:2048
	ds_read_b128 v[218:221], v218 offset:3072
	global_load_lds_dwordx4 v[222:223], off
	v_lshl_add_u64 v[222:223], v[224:225], 0, s[10:11]
	s_add_i32 m0, s37, 0x2000
	s_nop 0
	global_load_lds_dwordx4 v[222:223], off
	s_barrier
	s_waitcnt lgkmcnt(0)
	s_setprio 1
	s_waitcnt lgkmcnt(0)
	v_mfma_f32_16x16x32_bf16 v[116:119], v[206:209], v[174:177], v[116:119]
	v_mfma_f32_16x16x32_bf16 v[108:111], v[214:217], v[174:177], v[108:111]
	v_mfma_f32_16x16x32_bf16 v[100:103], v[206:209], v[182:185], v[100:103]
	v_mfma_f32_16x16x32_bf16 v[92:95], v[214:217], v[182:185], v[92:95]
	v_mfma_f32_16x16x32_bf16 v[84:87], v[206:209], v[190:193], v[84:87]
	v_mfma_f32_16x16x32_bf16 v[76:79], v[214:217], v[190:193], v[76:79]
	v_mfma_f32_16x16x32_bf16 v[68:71], v[206:209], v[198:201], v[68:71]
	v_mfma_f32_16x16x32_bf16 v[64:67], v[214:217], v[198:201], v[64:67]
	v_mfma_f32_16x16x32_bf16 v[116:119], v[210:213], v[178:181], v[116:119]
	v_mfma_f32_16x16x32_bf16 v[108:111], v[218:221], v[178:181], v[108:111]
	v_mfma_f32_16x16x32_bf16 v[100:103], v[210:213], v[186:189], v[100:103]
	v_mfma_f32_16x16x32_bf16 v[92:95], v[218:221], v[186:189], v[92:95]
	v_mfma_f32_16x16x32_bf16 v[84:87], v[210:213], v[194:197], v[84:87]
	v_mfma_f32_16x16x32_bf16 v[76:79], v[218:221], v[194:197], v[76:79]
	v_mfma_f32_16x16x32_bf16 v[68:71], v[210:213], v[202:205], v[68:71]
	v_mfma_f32_16x16x32_bf16 v[64:67], v[218:221], v[202:205], v[64:67]
	s_setprio 0
	s_mov_b32 m0, s51
	v_lshl_add_u64 v[222:223], v[226:227], 0, s[10:11]
	s_barrier
	ds_read_b128 v[174:177], v164 offset:49152
	ds_read_b128 v[178:181], v164 offset:50176
	ds_read_b128 v[182:185], v164 offset:51200
	ds_read_b128 v[186:189], v164 offset:52224
	ds_read_b128 v[190:193], v164 offset:53248
	ds_read_b128 v[194:197], v164 offset:54272
	ds_read_b128 v[198:201], v164 offset:55296
	ds_read_b128 v[202:205], v164 offset:56320
	global_load_lds_dwordx4 v[222:223], off
	v_lshl_add_u64 v[222:223], v[228:229], 0, s[10:11]
	s_mov_b32 m0, s52
	s_nop 0
	global_load_lds_dwordx4 v[222:223], off
	s_barrier
	s_waitcnt lgkmcnt(0)
	s_setprio 1
	s_waitcnt lgkmcnt(0)
	v_mfma_f32_16x16x32_bf16 v[60:63], v[142:145], v[174:177], v[60:63]
	v_mfma_f32_16x16x32_bf16 v[56:59], v[166:169], v[174:177], v[56:59]
	v_mfma_f32_16x16x32_bf16 v[48:51], v[142:145], v[182:185], v[48:51]
	v_mfma_f32_16x16x32_bf16 v[40:43], v[166:169], v[182:185], v[40:43]
	v_mfma_f32_16x16x32_bf16 v[32:35], v[142:145], v[190:193], v[32:35]
	v_mfma_f32_16x16x32_bf16 v[24:27], v[166:169], v[190:193], v[24:27]
	v_mfma_f32_16x16x32_bf16 v[12:15], v[142:145], v[198:201], v[12:15]
	v_mfma_f32_16x16x32_bf16 v[8:11], v[166:169], v[198:201], v[8:11]
	v_mfma_f32_16x16x32_bf16 v[60:63], v[146:149], v[178:181], v[60:63]
	v_mfma_f32_16x16x32_bf16 v[56:59], v[170:173], v[178:181], v[56:59]
	v_mfma_f32_16x16x32_bf16 v[48:51], v[146:149], v[186:189], v[48:51]
	v_mfma_f32_16x16x32_bf16 v[40:43], v[170:173], v[186:189], v[40:43]
	v_mfma_f32_16x16x32_bf16 v[32:35], v[146:149], v[194:197], v[32:35]
	v_mfma_f32_16x16x32_bf16 v[24:27], v[170:173], v[194:197], v[24:27]
	v_mfma_f32_16x16x32_bf16 v[12:15], v[146:149], v[202:205], v[12:15]
	v_mfma_f32_16x16x32_bf16 v[8:11], v[170:173], v[202:205], v[8:11]
	s_setprio 0
	s_barrier
	s_add_u32 s34, s34, 0x40080
	s_addc_u32 s35, s35, 0
	s_add_i32 s36, s36, s42
	v_lshl_add_u64 v[142:143], s[34:35], 0, v[130:131]
	s_mov_b32 m0, s36
	s_nop 0
	global_load_lds_dwordx4 v[142:143], off
	v_lshl_add_u64 v[142:143], s[34:35], 0, v[134:135]
	s_add_i32 m0, s36, 0x2000
	s_nop 0
	global_load_lds_dwordx4 v[142:143], off
	s_waitcnt vmcnt(6)
	s_barrier
	s_setprio 1
	v_mfma_f32_16x16x32_bf16 v[52:55], v[206:209], v[174:177], v[52:55]
	v_mfma_f32_16x16x32_bf16 v[44:47], v[214:217], v[174:177], v[44:47]
	v_mfma_f32_16x16x32_bf16 v[36:39], v[206:209], v[182:185], v[36:39]
	v_mfma_f32_16x16x32_bf16 v[28:31], v[214:217], v[182:185], v[28:31]
	v_mfma_f32_16x16x32_bf16 v[20:23], v[206:209], v[190:193], v[20:23]
	v_mfma_f32_16x16x32_bf16 v[16:19], v[214:217], v[190:193], v[16:19]
	v_mfma_f32_16x16x32_bf16 v[4:7], v[206:209], v[198:201], v[4:7]
	v_mfma_f32_16x16x32_bf16 v[0:3], v[214:217], v[198:201], v[0:3]
	v_mfma_f32_16x16x32_bf16 v[52:55], v[210:213], v[178:181], v[52:55]
	v_mfma_f32_16x16x32_bf16 v[44:47], v[218:221], v[178:181], v[44:47]
	v_mfma_f32_16x16x32_bf16 v[36:39], v[210:213], v[186:189], v[36:39]
	v_mfma_f32_16x16x32_bf16 v[28:31], v[218:221], v[186:189], v[28:31]
	v_mfma_f32_16x16x32_bf16 v[20:23], v[210:213], v[194:197], v[20:23]
	v_mfma_f32_16x16x32_bf16 v[16:19], v[218:221], v[194:197], v[16:19]
	v_mfma_f32_16x16x32_bf16 v[4:7], v[210:213], v[202:205], v[4:7]
	v_mfma_f32_16x16x32_bf16 v[0:3], v[218:221], v[202:205], v[0:3]
	s_setprio 0
	s_add_i32 s63, s63, 2
	s_add_u32 s30, s30, 0x100
	s_addc_u32 s31, s31, 0
	s_add_u32 s61, s61, 0x100
	s_addc_u32 s62, s62, 0
	s_cmp_gt_u32 s63, 13
	s_barrier
	s_cbranch_scc0 .LBB0_332
	v_add_u32_e32 v142, s60, v150
	s_cmp_lt_i32 s60, 0x8000
	v_readlane_b32 s60, v254, 0
	v_add_u32_e32 v144, s50, v152
	v_readlane_b32 s61, v254, 1
	v_ashrrev_i32_e32 v143, 31, v142
	s_mov_b64 s[36:37], s[60:61]
	v_ashrrev_i32_e32 v145, 31, v144
	v_lshlrev_b64 v[146:147], 10, v[142:143]
	s_cselect_b32 s31, s37, s56
	s_cselect_b32 s30, s36, s55
	v_lshl_add_u64 v[144:145], v[146:147], 0, v[144:145]
	v_lshl_add_u64 v[170:171], v[144:145], 2, s[30:31]
	global_load_dwordx4 v[146:149], v[170:171], off
	global_load_dwordx4 v[166:169], v[170:171], off offset:16
	global_load_dwordx4 v[178:181], v[170:171], off offset:512
	global_load_dwordx4 v[182:185], v[170:171], off offset:528
	v_lshl_add_u64 v[250:251], v[144:145], 0, s[12:13]
	v_lshl_add_u64 v[252:253], v[250:251], 2, s[30:31]
	global_load_dwordx4 v[186:189], v[252:253], off
	v_lshl_add_u64 v[250:251], v[144:145], 0, s[12:13]
	v_lshl_add_u64 v[252:253], v[250:251], 2, s[30:31]
	global_load_dwordx4 v[190:193], v[252:253], off offset:16
	v_lshl_add_u64 v[250:251], v[144:145], 0, s[12:13]
	v_lshl_add_u64 v[252:253], v[250:251], 2, s[30:31]
	global_load_dwordx4 v[194:197], v[252:253], off offset:512
	v_lshl_add_u64 v[250:251], v[144:145], 0, s[12:13]
	v_lshl_add_u64 v[252:253], v[250:251], 2, s[30:31]
	global_load_dwordx4 v[198:201], v[252:253], off offset:528
	v_lshl_add_u64 v[250:251], v[144:145], 0, s[14:15]
	v_lshl_add_u64 v[252:253], v[250:251], 2, s[30:31]
	global_load_dwordx4 v[202:205], v[252:253], off
	v_lshl_add_u64 v[250:251], v[144:145], 0, s[14:15]
	v_lshl_add_u64 v[252:253], v[250:251], 2, s[30:31]
	global_load_dwordx4 v[206:209], v[252:253], off offset:16
	v_lshl_add_u64 v[250:251], v[144:145], 0, s[14:15]
	v_lshl_add_u64 v[252:253], v[250:251], 2, s[30:31]
	global_load_dwordx4 v[210:213], v[252:253], off offset:512
	v_lshl_add_u64 v[250:251], v[144:145], 0, s[14:15]
	v_lshl_add_u64 v[252:253], v[250:251], 2, s[30:31]
	global_load_dwordx4 v[214:217], v[252:253], off offset:528
	v_readlane_b32 s34, v254, 56
	v_readlane_b32 s35, v254, 57
	v_lshl_add_u64 v[174:175], v[144:145], 0, s[12:13]
	v_lshl_add_u64 v[176:177], v[174:175], 2, s[30:31]
	v_lshl_add_u64 v[172:173], v[144:145], 1, s[34:35]
	v_lshl_add_u64 v[174:175], v[174:175], 1, s[34:35]
	v_readlane_b32 s62, v254, 2
	v_readlane_b32 s63, v254, 3
	v_readlane_b32 s64, v254, 4
	v_readlane_b32 s65, v254, 5
	v_readlane_b32 s66, v254, 6
	v_readlane_b32 s67, v254, 7
	v_readlane_b32 s68, v254, 8
	v_readlane_b32 s69, v254, 9
	v_readlane_b32 s70, v254, 10
	v_readlane_b32 s71, v254, 11
	v_readlane_b32 s72, v254, 12
	v_readlane_b32 s73, v254, 13
	v_readlane_b32 s74, v254, 14
	v_readlane_b32 s75, v254, 15
	s_waitcnt vmcnt(10)
	v_pk_add_f32 v[126:127], v[126:127], v[148:149]
	v_pk_add_f32 v[124:125], v[124:125], v[146:147]
	v_pk_add_f32 v[122:123], v[122:123], v[168:169]
	v_pk_add_f32 v[120:121], v[120:121], v[166:167]
	v_cvt_pk_bf16_f32 v146, v124, v125
	v_cvt_pk_bf16_f32 v147, v126, v127
	v_cvt_pk_bf16_f32 v149, v122, v123
	s_nop 0
	v_cvt_pk_bf16_f32 v148, v120, v121
	global_store_dwordx4 v[172:173], v[146:149], off
	s_nop 0
	s_waitcnt vmcnt(9)
	s_nop 1
	v_mov_b32_e32 v146, v178
	v_mov_b32_e32 v147, v179
	v_mov_b32_e32 v148, v180
	v_mov_b32_e32 v149, v181
	v_mov_b32_e32 v166, v182
	v_mov_b32_e32 v167, v183
	v_mov_b32_e32 v168, v184
	v_mov_b32_e32 v169, v185
	v_pk_add_f32 v[118:119], v[118:119], v[148:149]
	v_pk_add_f32 v[148:149], v[116:117], v[146:147]
	v_pk_add_f32 v[116:117], v[110:111], v[168:169]
	v_pk_add_f32 v[146:147], v[108:109], v[166:167]
	v_cvt_pk_bf16_f32 v108, v148, v149
	v_cvt_pk_bf16_f32 v109, v118, v119
	v_cvt_pk_bf16_f32 v111, v116, v117
	s_nop 0
	v_cvt_pk_bf16_f32 v110, v146, v147
	global_store_dwordx4 v[172:173], v[108:111], off offset:256
	s_nop 0
	s_waitcnt vmcnt(8)
	s_nop 1
	v_mov_b32_e32 v166, v186
	v_mov_b32_e32 v167, v187
	v_mov_b32_e32 v168, v188
	v_mov_b32_e32 v169, v189
	v_mov_b32_e32 v170, v190
	v_mov_b32_e32 v171, v191
	v_mov_b32_e32 v172, v192
	v_mov_b32_e32 v173, v193
	v_pk_add_f32 v[108:109], v[114:115], v[168:169]
	v_pk_add_f32 v[110:111], v[112:113], v[166:167]
	v_pk_add_f32 v[106:107], v[106:107], v[172:173]
	v_pk_add_f32 v[104:105], v[104:105], v[170:171]
	v_cvt_pk_bf16_f32 v112, v110, v111
	v_cvt_pk_bf16_f32 v113, v108, v109
	v_cvt_pk_bf16_f32 v115, v106, v107
	v_lshl_add_u64 v[170:171], v[144:145], 0, s[14:15]
	v_cvt_pk_bf16_f32 v114, v104, v105
	global_store_dwordx4 v[174:175], v[112:115], off
	s_nop 0
	v_lshl_add_u64 v[172:173], v[170:171], 2, s[30:31]
	v_lshl_add_u64 v[170:171], v[170:171], 1, s[34:35]
	s_waitcnt vmcnt(7)
	s_nop 1
	v_mov_b32_e32 v112, v194
	v_mov_b32_e32 v113, v195
	v_mov_b32_e32 v114, v196
	v_mov_b32_e32 v115, v197
	v_mov_b32_e32 v166, v198
	v_mov_b32_e32 v167, v199
	v_mov_b32_e32 v168, v200
	v_mov_b32_e32 v169, v201
	v_pk_add_f32 v[102:103], v[102:103], v[114:115]
	v_pk_add_f32 v[100:101], v[100:101], v[112:113]
	v_pk_add_f32 v[94:95], v[94:95], v[168:169]
	v_pk_add_f32 v[92:93], v[92:93], v[166:167]
	v_cvt_pk_bf16_f32 v112, v100, v101
	v_cvt_pk_bf16_f32 v113, v102, v103
	v_cvt_pk_bf16_f32 v115, v94, v95
	s_nop 0
	v_cvt_pk_bf16_f32 v114, v92, v93
	global_store_dwordx4 v[174:175], v[112:115], off offset:256
	s_nop 0
	s_waitcnt vmcnt(6)
	s_nop 1
	v_mov_b32_e32 v112, v202
	v_mov_b32_e32 v113, v203
	v_mov_b32_e32 v114, v204
	v_mov_b32_e32 v115, v205
	v_mov_b32_e32 v166, v206
	v_mov_b32_e32 v167, v207
	v_mov_b32_e32 v168, v208
	v_mov_b32_e32 v169, v209
	v_pk_add_f32 v[98:99], v[98:99], v[114:115]
	v_pk_add_f32 v[96:97], v[96:97], v[112:113]
	v_pk_add_f32 v[90:91], v[90:91], v[168:169]
	v_pk_add_f32 v[88:89], v[88:89], v[166:167]
	v_cvt_pk_bf16_f32 v112, v96, v97
	v_cvt_pk_bf16_f32 v113, v98, v99
	v_cvt_pk_bf16_f32 v115, v90, v91
	s_nop 0
	v_cvt_pk_bf16_f32 v114, v88, v89
	global_store_dwordx4 v[170:171], v[112:115], off
	s_nop 0
	v_lshl_add_u64 v[172:173], v[144:145], 0, s[16:17]
	v_lshl_add_u64 v[174:175], v[172:173], 2, s[30:31]
	s_waitcnt vmcnt(5)
	s_nop 1
	v_mov_b32_e32 v112, v210
	v_mov_b32_e32 v113, v211
	v_mov_b32_e32 v114, v212
	v_mov_b32_e32 v115, v213
	v_mov_b32_e32 v166, v214
	v_mov_b32_e32 v167, v215
	v_mov_b32_e32 v168, v216
	v_mov_b32_e32 v169, v217
	v_pk_add_f32 v[86:87], v[86:87], v[114:115]
	v_pk_add_f32 v[84:85], v[84:85], v[112:113]
	v_pk_add_f32 v[78:79], v[78:79], v[168:169]
	v_pk_add_f32 v[76:77], v[76:77], v[166:167]
	v_cvt_pk_bf16_f32 v112, v84, v85
	v_cvt_pk_bf16_f32 v113, v86, v87
	v_cvt_pk_bf16_f32 v115, v78, v79
	v_mul_f32_e32 v85, v85, v85
	v_cvt_pk_bf16_f32 v114, v76, v77
	global_store_dwordx4 v[170:171], v[112:115], off offset:256
	global_load_dwordx4 v[112:115], v[174:175], off
	s_nop 0
	global_load_dwordx4 v[166:169], v[174:175], off offset:16
	v_lshl_add_u64 v[170:171], v[172:173], 1, s[34:35]
	v_lshl_add_u64 v[172:173], v[144:145], 0, s[18:19]
	v_fmac_f32_e32 v85, v84, v84
	v_fmac_f32_e32 v85, v86, v86
	v_fmac_f32_e32 v85, v87, v87
	v_fmac_f32_e32 v85, v76, v76
	v_fmac_f32_e32 v85, v77, v77
	v_fmac_f32_e32 v85, v78, v78
	v_fmac_f32_e32 v85, v79, v79
	s_waitcnt vmcnt(0)
	v_pk_add_f32 v[82:83], v[82:83], v[114:115]
	v_pk_add_f32 v[80:81], v[80:81], v[112:113]
	v_pk_add_f32 v[74:75], v[74:75], v[168:169]
	v_pk_add_f32 v[72:73], v[72:73], v[166:167]
	v_cvt_pk_bf16_f32 v112, v80, v81
	v_cvt_pk_bf16_f32 v113, v82, v83
	v_cvt_pk_bf16_f32 v115, v74, v75
	v_mul_f32_e32 v86, v81, v81
	v_cvt_pk_bf16_f32 v114, v72, v73
	global_store_dwordx4 v[170:171], v[112:115], off
	global_load_dwordx4 v[112:115], v[174:175], off offset:512
	s_nop 0
	global_load_dwordx4 v[166:169], v[174:175], off offset:528
	v_lshl_add_u64 v[174:175], v[172:173], 2, s[30:31]
	v_fmac_f32_e32 v86, v80, v80
	v_fmac_f32_e32 v86, v82, v82
	v_fmac_f32_e32 v86, v83, v83
	v_fmac_f32_e32 v86, v72, v72
	v_fmac_f32_e32 v86, v73, v73
	v_fmac_f32_e32 v86, v74, v74
	v_fmac_f32_e32 v86, v75, v75
	s_waitcnt vmcnt(0)
	v_pk_add_f32 v[70:71], v[70:71], v[114:115]
	v_pk_add_f32 v[68:69], v[68:69], v[112:113]
	v_pk_add_f32 v[66:67], v[66:67], v[168:169]
	v_pk_add_f32 v[64:65], v[64:65], v[166:167]
	v_cvt_pk_bf16_f32 v112, v68, v69
	v_cvt_pk_bf16_f32 v113, v70, v71
	v_cvt_pk_bf16_f32 v115, v66, v67
	s_nop 0
	v_cvt_pk_bf16_f32 v114, v64, v65
	global_store_dwordx4 v[170:171], v[112:115], off offset:256
	global_load_dwordx4 v[112:115], v[174:175], off
	s_nop 0
	global_load_dwordx4 v[166:169], v[174:175], off offset:16
	v_lshl_add_u64 v[170:171], v[172:173], 1, s[34:35]
	v_lshl_add_u64 v[172:173], v[144:145], 0, s[20:21]
	s_waitcnt vmcnt(0)
	v_pk_add_f32 v[62:63], v[62:63], v[114:115]
	v_pk_add_f32 v[60:61], v[60:61], v[112:113]
	v_pk_add_f32 v[58:59], v[58:59], v[168:169]
	v_pk_add_f32 v[56:57], v[56:57], v[166:167]
	v_cvt_pk_bf16_f32 v112, v60, v61
	v_cvt_pk_bf16_f32 v113, v62, v63
	v_cvt_pk_bf16_f32 v115, v58, v59
	s_nop 0
	v_cvt_pk_bf16_f32 v114, v56, v57
	global_store_dwordx4 v[170:171], v[112:115], off
	global_load_dwordx4 v[112:115], v[174:175], off offset:512
	s_nop 0
	global_load_dwordx4 v[166:169], v[174:175], off offset:528
	v_lshl_add_u64 v[174:175], v[172:173], 2, s[30:31]
	s_waitcnt vmcnt(0)
	v_pk_add_f32 v[54:55], v[54:55], v[114:115]
	v_pk_add_f32 v[52:53], v[52:53], v[112:113]
	v_pk_add_f32 v[46:47], v[46:47], v[168:169]
	v_pk_add_f32 v[44:45], v[44:45], v[166:167]
	v_cvt_pk_bf16_f32 v112, v52, v53
	v_cvt_pk_bf16_f32 v113, v54, v55
	v_cvt_pk_bf16_f32 v115, v46, v47
	s_nop 0
	v_cvt_pk_bf16_f32 v114, v44, v45
	global_store_dwordx4 v[170:171], v[112:115], off offset:256
	global_load_dwordx4 v[112:115], v[174:175], off
	s_nop 0
	global_load_dwordx4 v[166:169], v[174:175], off offset:16
	v_lshl_add_u64 v[170:171], v[172:173], 1, s[34:35]
	v_lshl_add_u64 v[172:173], v[144:145], 0, s[22:23]
	v_lshl_add_u64 v[144:145], v[144:145], 0, s[24:25]
	s_waitcnt vmcnt(0)
	v_pk_add_f32 v[50:51], v[50:51], v[114:115]
	v_pk_add_f32 v[48:49], v[48:49], v[112:113]
	v_pk_add_f32 v[42:43], v[42:43], v[168:169]
	v_pk_add_f32 v[40:41], v[40:41], v[166:167]
	v_cvt_pk_bf16_f32 v112, v48, v49
	v_cvt_pk_bf16_f32 v113, v50, v51
	v_cvt_pk_bf16_f32 v115, v42, v43
	s_nop 0
	v_cvt_pk_bf16_f32 v114, v40, v41
	global_store_dwordx4 v[170:171], v[112:115], off
	global_load_dwordx4 v[112:115], v[174:175], off offset:512
	s_nop 0
	global_load_dwordx4 v[166:169], v[174:175], off offset:528
	v_lshl_add_u64 v[174:175], v[172:173], 2, s[30:31]
	s_waitcnt vmcnt(0)
	v_pk_add_f32 v[38:39], v[38:39], v[114:115]
	v_pk_add_f32 v[36:37], v[36:37], v[112:113]
	v_pk_add_f32 v[30:31], v[30:31], v[168:169]
	v_pk_add_f32 v[28:29], v[28:29], v[166:167]
	v_cvt_pk_bf16_f32 v112, v36, v37
	v_cvt_pk_bf16_f32 v113, v38, v39
	v_cvt_pk_bf16_f32 v115, v30, v31
	v_mul_f32_e32 v37, v37, v37
	v_cvt_pk_bf16_f32 v114, v28, v29
	global_store_dwordx4 v[170:171], v[112:115], off offset:256
	global_load_dwordx4 v[112:115], v[174:175], off
	s_nop 0
	global_load_dwordx4 v[166:169], v[174:175], off offset:16
	v_lshl_add_u64 v[170:171], v[172:173], 1, s[34:35]
	v_lshl_add_u64 v[172:173], v[144:145], 2, s[30:31]
	v_fmac_f32_e32 v37, v36, v36
	v_fmac_f32_e32 v37, v38, v38
	v_fmac_f32_e32 v37, v39, v39
	v_fmac_f32_e32 v37, v28, v28
	v_fmac_f32_e32 v37, v29, v29
	v_fmac_f32_e32 v37, v30, v30
	v_fmac_f32_e32 v37, v31, v31
	s_waitcnt vmcnt(0)
	v_pk_add_f32 v[34:35], v[34:35], v[114:115]
	v_pk_add_f32 v[32:33], v[32:33], v[112:113]
	v_pk_add_f32 v[26:27], v[26:27], v[168:169]
	v_pk_add_f32 v[24:25], v[24:25], v[166:167]
	v_cvt_pk_bf16_f32 v112, v32, v33
	v_cvt_pk_bf16_f32 v113, v34, v35
	v_cvt_pk_bf16_f32 v115, v26, v27
	v_mul_f32_e32 v29, v33, v33
	v_cvt_pk_bf16_f32 v114, v24, v25
	global_store_dwordx4 v[170:171], v[112:115], off
	global_load_dwordx4 v[112:115], v[174:175], off offset:512
	s_nop 0
	global_load_dwordx4 v[166:169], v[174:175], off offset:528
	v_fmac_f32_e32 v29, v32, v32
	v_fmac_f32_e32 v29, v34, v34
	v_fmac_f32_e32 v29, v35, v35
	v_fmac_f32_e32 v29, v24, v24
	v_fmac_f32_e32 v29, v25, v25
	v_fmac_f32_e32 v29, v26, v26
	v_fmac_f32_e32 v29, v27, v27
	s_waitcnt vmcnt(0)
	v_pk_add_f32 v[174:175], v[22:23], v[114:115]
	v_pk_add_f32 v[176:177], v[20:21], v[112:113]
	v_pk_add_f32 v[168:169], v[18:19], v[168:169]
	v_pk_add_f32 v[166:167], v[16:17], v[166:167]
	v_cvt_pk_bf16_f32 v16, v176, v177
	v_cvt_pk_bf16_f32 v17, v174, v175
	v_cvt_pk_bf16_f32 v19, v168, v169
	v_mul_f32_e32 v24, v177, v177
	v_cvt_pk_bf16_f32 v18, v166, v167
	global_store_dwordx4 v[170:171], v[16:19], off offset:256
	global_load_dwordx4 v[20:23], v[172:173], off
	global_load_dwordx4 v[112:115], v[172:173], off offset:16
	v_mul_f32_e32 v19, v101, v101
	v_fmac_f32_e32 v19, v100, v100
	v_fmac_f32_e32 v19, v102, v102
	v_fmac_f32_e32 v19, v103, v103
	v_fmac_f32_e32 v19, v92, v92
	v_fmac_f32_e32 v19, v93, v93
	v_lshl_add_u64 v[92:93], v[144:145], 1, s[34:35]
	v_fmac_f32_e32 v24, v176, v176
	v_fmac_f32_e32 v24, v174, v174
	v_fmac_f32_e32 v24, v175, v175
	v_fmac_f32_e32 v24, v166, v166
	v_fmac_f32_e32 v24, v167, v167
	v_fmac_f32_e32 v24, v168, v168
	v_fmac_f32_e32 v24, v169, v169
	v_add_f32_e32 v26, v29, v24
	v_mul_f32_e32 v16, v125, v125
	v_mul_f32_e32 v17, v149, v149
	v_mul_f32_e32 v18, v111, v111
	v_fmac_f32_e32 v19, v94, v94
	v_mul_f32_e32 v94, v97, v97
	v_fmac_f32_e32 v16, v124, v124
	v_fmac_f32_e32 v17, v148, v148
	v_fmac_f32_e32 v18, v110, v110
	v_fmac_f32_e32 v94, v96, v96
	v_fmac_f32_e32 v16, v126, v126
	v_fmac_f32_e32 v17, v118, v118
	v_fmac_f32_e32 v18, v108, v108
	v_fmac_f32_e32 v94, v98, v98
	v_fmac_f32_e32 v16, v127, v127
	v_fmac_f32_e32 v17, v119, v119
	v_fmac_f32_e32 v18, v109, v109
	v_fmac_f32_e32 v94, v99, v99
	v_fmac_f32_e32 v16, v120, v120
	v_fmac_f32_e32 v17, v146, v146
	v_fmac_f32_e32 v18, v104, v104
	v_fmac_f32_e32 v94, v88, v88
	v_fmac_f32_e32 v16, v121, v121
	v_fmac_f32_e32 v17, v147, v147
	v_fmac_f32_e32 v18, v105, v105
	v_fmac_f32_e32 v94, v89, v89
	v_fmac_f32_e32 v16, v122, v122
	v_fmac_f32_e32 v17, v116, v116
	v_fmac_f32_e32 v18, v106, v106
	v_fmac_f32_e32 v94, v90, v90
	v_fmac_f32_e32 v16, v123, v123
	v_fmac_f32_e32 v17, v117, v117
	v_fmac_f32_e32 v18, v107, v107
	v_fmac_f32_e32 v19, v95, v95
	v_fmac_f32_e32 v94, v91, v91
	v_add_f32_e32 v16, v16, v17
	v_add_f32_e32 v18, v18, v19
	v_add_f32_e32 v84, v94, v85
	ds_bpermute_b32 v17, v153, v16
	ds_bpermute_b32 v19, v153, v18
	ds_bpermute_b32 v85, v153, v84
	ds_bpermute_b32 v27, v153, v26
	s_waitcnt lgkmcnt(0)
	v_add_f32_e32 v16, v16, v17
	v_add_f32_e32 v18, v18, v19
	ds_bpermute_b32 v17, v154, v16
	ds_bpermute_b32 v19, v154, v18
	s_waitcnt vmcnt(1)
	v_pk_add_f32 v[14:15], v[14:15], v[22:23]
	v_pk_add_f32 v[72:73], v[12:13], v[20:21]
	s_waitcnt vmcnt(0)
	v_pk_add_f32 v[80:81], v[10:11], v[114:115]
	v_pk_add_f32 v[82:83], v[8:9], v[112:113]
	v_cvt_pk_bf16_f32 v8, v72, v73
	v_cvt_pk_bf16_f32 v9, v14, v15
	v_cvt_pk_bf16_f32 v11, v80, v81
	v_mul_f32_e32 v29, v73, v73
	v_cvt_pk_bf16_f32 v10, v82, v83
	global_store_dwordx4 v[92:93], v[8:11], off
	global_load_dwordx4 v[20:23], v[172:173], off offset:528
	global_load_dwordx4 v[76:79], v[172:173], off offset:512
	v_mul_f32_e32 v8, v69, v69
	v_fmac_f32_e32 v8, v68, v68
	v_fmac_f32_e32 v8, v70, v70
	v_fmac_f32_e32 v8, v71, v71
	v_fmac_f32_e32 v8, v64, v64
	v_fmac_f32_e32 v8, v65, v65
	v_fmac_f32_e32 v8, v66, v66
	v_fmac_f32_e32 v8, v67, v67
	v_add_f32_e32 v10, v86, v8
	v_mul_f32_e32 v8, v61, v61
	v_mul_f32_e32 v9, v53, v53
	v_fmac_f32_e32 v8, v60, v60
	v_fmac_f32_e32 v9, v52, v52
	v_fmac_f32_e32 v8, v62, v62
	v_fmac_f32_e32 v9, v54, v54
	v_fmac_f32_e32 v8, v63, v63
	v_fmac_f32_e32 v9, v55, v55
	v_fmac_f32_e32 v8, v56, v56
	v_fmac_f32_e32 v9, v44, v44
	v_fmac_f32_e32 v8, v57, v57
	v_fmac_f32_e32 v9, v45, v45
	v_fmac_f32_e32 v8, v58, v58
	v_fmac_f32_e32 v9, v46, v46
	v_fmac_f32_e32 v8, v59, v59
	v_fmac_f32_e32 v9, v47, v47
	v_add_f32_e32 v12, v8, v9
	ds_bpermute_b32 v13, v153, v12
	v_fmac_f32_e32 v29, v72, v72
	v_fmac_f32_e32 v29, v14, v14
	v_fmac_f32_e32 v29, v15, v15
	v_fmac_f32_e32 v29, v82, v82
	s_waitcnt lgkmcnt(0)
	v_add_f32_e32 v12, v12, v13
	v_mul_f32_e32 v13, v49, v49
	v_fmac_f32_e32 v13, v48, v48
	v_fmac_f32_e32 v13, v50, v50
	v_fmac_f32_e32 v13, v51, v51
	v_fmac_f32_e32 v13, v40, v40
	v_fmac_f32_e32 v13, v41, v41
	v_fmac_f32_e32 v29, v83, v83
	v_fmac_f32_e32 v13, v42, v42
	v_fmac_f32_e32 v29, v80, v80
	v_fmac_f32_e32 v13, v43, v43
	v_fmac_f32_e32 v29, v81, v81
	v_add_f32_e32 v13, v13, v37
	ds_bpermute_b32 v11, v153, v10
	ds_bpermute_b32 v28, v153, v13
	v_add_f32_e32 v8, v84, v85
	ds_bpermute_b32 v9, v154, v8
	s_waitcnt lgkmcnt(2)
	v_add_f32_e32 v10, v10, v11
	ds_bpermute_b32 v11, v154, v10
	s_waitcnt vmcnt(1)
	v_pk_add_f32 v[24:25], v[2:3], v[22:23]
	s_waitcnt vmcnt(0)
	v_pk_add_f32 v[4:5], v[4:5], v[76:77]
	v_pk_add_f32 v[22:23], v[0:1], v[20:21]
	v_mul_f32_e32 v0, v5, v5
	v_pk_add_f32 v[14:15], v[6:7], v[78:79]
	v_fmac_f32_e32 v0, v4, v4
	v_fmac_f32_e32 v0, v14, v14
	v_fmac_f32_e32 v0, v15, v15
	v_fmac_f32_e32 v0, v22, v22
	v_fmac_f32_e32 v0, v23, v23
	v_fmac_f32_e32 v0, v24, v24
	v_fmac_f32_e32 v0, v25, v25
	v_cvt_pk_bf16_f32 v20, v4, v5
	v_add_f32_e32 v5, v29, v0
	ds_bpermute_b32 v6, v153, v5
	s_waitcnt lgkmcnt(3)
	v_add_f32_e32 v1, v13, v28
	v_add_f32_e32 v3, v26, v27
	ds_bpermute_b32 v0, v154, v12
	ds_bpermute_b32 v2, v154, v1
	s_waitcnt lgkmcnt(2)
	v_add_f32_e32 v5, v5, v6
	ds_bpermute_b32 v4, v154, v3
	ds_bpermute_b32 v6, v154, v5
	v_cvt_pk_bf16_f32 v21, v14, v15
	v_cvt_pk_bf16_f32 v22, v22, v23
	v_cvt_pk_bf16_f32 v23, v24, v25
	global_store_dwordx4 v[92:93], v[20:23], off offset:256
	s_and_saveexec_b64 s[30:31], s[0:1]
	s_cbranch_execz .LBB0_335
	s_waitcnt lgkmcnt(0)
	v_add_f32_e32 v5, v5, v6
	v_add_f32_e32 v3, v3, v4
	v_add_f32_e32 v1, v1, v2
	v_add_f32_e32 v2, v10, v11
	v_add_f32_e32 v4, v8, v9
	v_add_f32_e32 v6, v18, v19
	v_add_f32_e32 v7, v16, v17
	v_add_u32_e32 v8, s53, v155
	v_add_f32_e32 v0, v12, v0
	ds_write2st64_b32 v8, v7, v6 offset1:1
	ds_write2st64_b32 v8, v4, v2 offset0:2 offset1:3
	v_add_u32_e32 v2, s53, v159
	ds_write2st64_b32 v2, v0, v1 offset1:1
	ds_write2st64_b32 v2, v3, v5 offset0:2 offset1:3

.LBB0_470:
	s_add_u32 s22, s48, 0xfff00080
	s_addc_u32 s23, s49, -1
	s_add_i32 s86, 0, 0x10000
	v_add_u32_e32 v172, s86, v149
	ds_read_b128 v[144:147], v172
	ds_read_b128 v[164:167], v172 offset:1024
	ds_read_b128 v[168:171], v172 offset:2048
	ds_read_b128 v[172:175], v172 offset:3072
	s_cmp_eq_u32 s60, 60
	s_cselect_b32 s53, s45, s23
	s_cselect_b32 s52, s44, s22
	s_cselect_b32 s51, s47, s19
	s_cselect_b32 s50, s46, s18
	v_lshl_add_u64 v[212:213], s[48:49], 0, v[140:141]
	s_add_i32 m0, s75, 0xc000
	ds_read_b128 v[176:179], v163
	ds_read_b128 v[180:183], v163 offset:1024
	ds_read_b128 v[184:187], v163 offset:2048
	ds_read_b128 v[188:191], v163 offset:3072
	ds_read_b128 v[192:195], v163 offset:4096
	ds_read_b128 v[200:203], v163 offset:5120
	ds_read_b128 v[204:207], v163 offset:6144
	ds_read_b128 v[208:211], v163 offset:7168
	global_load_lds_dwordx4 v[212:213], off
	v_lshl_add_u64 v[212:213], s[48:49], 0, v[142:143]
	s_add_i32 m0, s75, 0xe000
	s_nop 0
	global_load_lds_dwordx4 v[212:213], off
	s_waitcnt lgkmcnt(8)
	s_barrier
	s_waitcnt lgkmcnt(0)
	s_setprio 1
	s_waitcnt lgkmcnt(0)
	v_mfma_f32_16x16x32_bf16 v[124:127], v[144:147], v[176:179], v[124:127]
	v_mfma_f32_16x16x32_bf16 v[120:123], v[168:171], v[176:179], v[120:123]
	v_mfma_f32_16x16x32_bf16 v[108:111], v[144:147], v[184:187], v[108:111]
	v_mfma_f32_16x16x32_bf16 v[104:107], v[168:171], v[184:187], v[104:107]
	v_mfma_f32_16x16x32_bf16 v[92:95], v[144:147], v[192:195], v[92:95]
	v_mfma_f32_16x16x32_bf16 v[88:91], v[168:171], v[192:195], v[88:91]
	v_mfma_f32_16x16x32_bf16 v[76:79], v[144:147], v[204:207], v[76:79]
	v_mfma_f32_16x16x32_bf16 v[72:75], v[168:171], v[204:207], v[72:75]
	v_mfma_f32_16x16x32_bf16 v[124:127], v[164:167], v[180:183], v[124:127]
	v_mfma_f32_16x16x32_bf16 v[120:123], v[172:175], v[180:183], v[120:123]
	v_mfma_f32_16x16x32_bf16 v[108:111], v[164:167], v[188:191], v[108:111]
	v_mfma_f32_16x16x32_bf16 v[104:107], v[172:175], v[188:191], v[104:107]
	v_mfma_f32_16x16x32_bf16 v[92:95], v[164:167], v[200:203], v[92:95]
	v_mfma_f32_16x16x32_bf16 v[88:91], v[172:175], v[200:203], v[88:91]
	v_mfma_f32_16x16x32_bf16 v[76:79], v[164:167], v[208:211], v[76:79]
	v_mfma_f32_16x16x32_bf16 v[72:75], v[172:175], v[208:211], v[72:75]
	s_setprio 0
	s_barrier
	s_add_i32 s87, 0, 0x14000
	s_add_i32 s22, s86, s74
	v_add_u32_e32 v224, s87, v149
	v_lshl_add_u64 v[228:229], s[50:51], 0, v[138:139]
	s_mov_b32 m0, s22
	ds_read_b128 v[212:215], v224
	ds_read_b128 v[216:219], v224 offset:1024
	ds_read_b128 v[220:223], v224 offset:2048
	ds_read_b128 v[224:227], v224 offset:3072
	global_load_lds_dwordx4 v[228:229], off
	v_lshl_add_u64 v[230:231], s[50:51], 0, v[134:135]
	s_add_i32 m0, s22, 0x2000
	s_nop 0
	global_load_lds_dwordx4 v[230:231], off
	s_barrier
	s_waitcnt lgkmcnt(0)
	s_setprio 1
	s_waitcnt lgkmcnt(0)
	v_mfma_f32_16x16x32_bf16 v[116:119], v[212:215], v[176:179], v[116:119]
	v_mfma_f32_16x16x32_bf16 v[112:115], v[220:223], v[176:179], v[112:115]
	v_mfma_f32_16x16x32_bf16 v[100:103], v[212:215], v[184:187], v[100:103]
	v_mfma_f32_16x16x32_bf16 v[96:99], v[220:223], v[184:187], v[96:99]
	v_mfma_f32_16x16x32_bf16 v[84:87], v[212:215], v[192:195], v[84:87]
	v_mfma_f32_16x16x32_bf16 v[80:83], v[220:223], v[192:195], v[80:83]
	v_mfma_f32_16x16x32_bf16 v[68:71], v[212:215], v[204:207], v[68:71]
	v_mfma_f32_16x16x32_bf16 v[64:67], v[220:223], v[204:207], v[64:67]
	v_mfma_f32_16x16x32_bf16 v[116:119], v[216:219], v[180:183], v[116:119]
	v_mfma_f32_16x16x32_bf16 v[112:115], v[224:227], v[180:183], v[112:115]
	v_mfma_f32_16x16x32_bf16 v[100:103], v[216:219], v[188:191], v[100:103]
	v_mfma_f32_16x16x32_bf16 v[96:99], v[224:227], v[188:191], v[96:99]
	v_mfma_f32_16x16x32_bf16 v[84:87], v[216:219], v[200:203], v[84:87]
	v_mfma_f32_16x16x32_bf16 v[80:83], v[224:227], v[200:203], v[80:83]
	v_mfma_f32_16x16x32_bf16 v[68:71], v[216:219], v[208:211], v[68:71]
	v_mfma_f32_16x16x32_bf16 v[64:67], v[224:227], v[208:211], v[64:67]
	s_setprio 0
	s_mov_b32 m0, s75
	v_lshl_add_u64 v[232:233], s[52:53], 0, v[128:129]
	s_barrier
	ds_read_b128 v[176:179], v163 offset:16384
	ds_read_b128 v[180:183], v163 offset:17408
	ds_read_b128 v[184:187], v163 offset:18432
	ds_read_b128 v[188:191], v163 offset:19456
	ds_read_b128 v[192:195], v163 offset:20480
	ds_read_b128 v[200:203], v163 offset:21504
	ds_read_b128 v[204:207], v163 offset:22528
	ds_read_b128 v[208:211], v163 offset:23552
	global_load_lds_dwordx4 v[232:233], off
	v_lshl_add_u64 v[234:235], s[52:53], 0, v[136:137]
	s_mov_b32 m0, s76
	s_nop 0
	global_load_lds_dwordx4 v[234:235], off
	s_barrier
	s_waitcnt lgkmcnt(0)
	s_setprio 1
	s_waitcnt lgkmcnt(0)
	v_mfma_f32_16x16x32_bf16 v[60:63], v[144:147], v[176:179], v[60:63]
	v_mfma_f32_16x16x32_bf16 v[56:59], v[168:171], v[176:179], v[56:59]
	v_mfma_f32_16x16x32_bf16 v[44:47], v[144:147], v[184:187], v[44:47]
	v_mfma_f32_16x16x32_bf16 v[40:43], v[168:171], v[184:187], v[40:43]
	v_mfma_f32_16x16x32_bf16 v[28:31], v[144:147], v[192:195], v[28:31]
	v_mfma_f32_16x16x32_bf16 v[24:27], v[168:171], v[192:195], v[24:27]
	v_mfma_f32_16x16x32_bf16 v[12:15], v[144:147], v[204:207], v[12:15]
	v_mfma_f32_16x16x32_bf16 v[8:11], v[168:171], v[204:207], v[8:11]
	v_mfma_f32_16x16x32_bf16 v[60:63], v[164:167], v[180:183], v[60:63]
	v_mfma_f32_16x16x32_bf16 v[56:59], v[172:175], v[180:183], v[56:59]
	v_mfma_f32_16x16x32_bf16 v[44:47], v[164:167], v[188:191], v[44:47]
	v_mfma_f32_16x16x32_bf16 v[40:43], v[172:175], v[188:191], v[40:43]
	v_mfma_f32_16x16x32_bf16 v[28:31], v[164:167], v[200:203], v[28:31]
	v_mfma_f32_16x16x32_bf16 v[24:27], v[172:175], v[200:203], v[24:27]
	v_mfma_f32_16x16x32_bf16 v[12:15], v[164:167], v[208:211], v[12:15]
	v_mfma_f32_16x16x32_bf16 v[8:11], v[172:175], v[208:211], v[8:11]
	s_setprio 0
	s_barrier
	s_add_u32 s22, s50, 0x100000
	s_addc_u32 s23, s51, 0
	s_add_i32 s86, s87, s74
	v_lshl_add_u64 v[144:145], s[22:23], 0, v[138:139]
	s_mov_b32 m0, s86
	s_nop 0
	global_load_lds_dwordx4 v[144:145], off
	v_lshl_add_u64 v[144:145], s[22:23], 0, v[134:135]
	s_add_i32 m0, s86, 0x2000
	s_nop 0
	global_load_lds_dwordx4 v[144:145], off
	s_waitcnt vmcnt(6)
	s_barrier
	s_setprio 1
	v_mfma_f32_16x16x32_bf16 v[52:55], v[212:215], v[176:179], v[52:55]
	v_mfma_f32_16x16x32_bf16 v[48:51], v[220:223], v[176:179], v[48:51]
	v_mfma_f32_16x16x32_bf16 v[36:39], v[212:215], v[184:187], v[36:39]
	v_mfma_f32_16x16x32_bf16 v[32:35], v[220:223], v[184:187], v[32:35]
	v_mfma_f32_16x16x32_bf16 v[20:23], v[212:215], v[192:195], v[20:23]
	v_mfma_f32_16x16x32_bf16 v[16:19], v[220:223], v[192:195], v[16:19]
	v_mfma_f32_16x16x32_bf16 v[4:7], v[212:215], v[204:207], v[4:7]
	v_mfma_f32_16x16x32_bf16 v[0:3], v[220:223], v[204:207], v[0:3]
	v_mfma_f32_16x16x32_bf16 v[52:55], v[216:219], v[180:183], v[52:55]
	v_mfma_f32_16x16x32_bf16 v[48:51], v[224:227], v[180:183], v[48:51]
	v_mfma_f32_16x16x32_bf16 v[36:39], v[216:219], v[188:191], v[36:39]
	v_mfma_f32_16x16x32_bf16 v[32:35], v[224:227], v[188:191], v[32:35]
	v_mfma_f32_16x16x32_bf16 v[20:23], v[216:219], v[200:203], v[20:23]
	v_mfma_f32_16x16x32_bf16 v[16:19], v[224:227], v[200:203], v[16:19]
	v_mfma_f32_16x16x32_bf16 v[4:7], v[216:219], v[208:211], v[4:7]
	v_mfma_f32_16x16x32_bf16 v[0:3], v[224:227], v[208:211], v[0:3]
	s_setprio 0
	s_add_i32 s86, 0, 0x18000
	v_add_u32_e32 v172, s86, v149
	s_barrier
	ds_read_b128 v[144:147], v172
	ds_read_b128 v[164:167], v172 offset:1024
	ds_read_b128 v[168:171], v172 offset:2048
	ds_read_b128 v[172:175], v172 offset:3072
	s_add_u32 s22, s52, 0x100000
	s_addc_u32 s23, s53, 0
	s_mov_b32 m0, s77
	v_lshl_add_u64 v[212:213], s[22:23], 0, v[128:129]
	ds_read_b128 v[176:179], v163 offset:32768
	ds_read_b128 v[180:183], v163 offset:33792
	ds_read_b128 v[184:187], v163 offset:34816
	ds_read_b128 v[188:191], v163 offset:35840
	ds_read_b128 v[192:195], v163 offset:36864
	ds_read_b128 v[200:203], v163 offset:37888
	ds_read_b128 v[204:207], v163 offset:38912
	ds_read_b128 v[208:211], v163 offset:39936
	global_load_lds_dwordx4 v[212:213], off
	v_lshl_add_u64 v[212:213], s[22:23], 0, v[136:137]
	s_mov_b32 m0, s78
	s_nop 0
	global_load_lds_dwordx4 v[212:213], off
	s_waitcnt lgkmcnt(8)
	s_barrier
	s_waitcnt lgkmcnt(0)
	s_setprio 1
	s_waitcnt lgkmcnt(0)
	v_mfma_f32_16x16x32_bf16 v[124:127], v[144:147], v[176:179], v[124:127]
	v_mfma_f32_16x16x32_bf16 v[120:123], v[168:171], v[176:179], v[120:123]
	v_mfma_f32_16x16x32_bf16 v[108:111], v[144:147], v[184:187], v[108:111]
	v_mfma_f32_16x16x32_bf16 v[104:107], v[168:171], v[184:187], v[104:107]
	v_mfma_f32_16x16x32_bf16 v[92:95], v[144:147], v[192:195], v[92:95]
	v_mfma_f32_16x16x32_bf16 v[88:91], v[168:171], v[192:195], v[88:91]
	v_mfma_f32_16x16x32_bf16 v[76:79], v[144:147], v[204:207], v[76:79]
	v_mfma_f32_16x16x32_bf16 v[72:75], v[168:171], v[204:207], v[72:75]
	v_mfma_f32_16x16x32_bf16 v[124:127], v[164:167], v[180:183], v[124:127]
	v_mfma_f32_16x16x32_bf16 v[120:123], v[172:175], v[180:183], v[120:123]
	v_mfma_f32_16x16x32_bf16 v[108:111], v[164:167], v[188:191], v[108:111]
	v_mfma_f32_16x16x32_bf16 v[104:107], v[172:175], v[188:191], v[104:107]
	v_mfma_f32_16x16x32_bf16 v[92:95], v[164:167], v[200:203], v[92:95]
	v_mfma_f32_16x16x32_bf16 v[88:91], v[172:175], v[200:203], v[88:91]
	v_mfma_f32_16x16x32_bf16 v[76:79], v[164:167], v[208:211], v[76:79]
	v_mfma_f32_16x16x32_bf16 v[72:75], v[172:175], v[208:211], v[72:75]
	s_setprio 0
	s_barrier
	s_add_i32 s52, 0, 0x1c000
	s_add_i32 s22, s86, s74
	v_add_u32_e32 v224, s52, v149
	v_lshl_add_u64 v[228:229], v[228:229], 0, s[40:41]
	s_mov_b32 m0, s22
	ds_read_b128 v[212:215], v224
	ds_read_b128 v[216:219], v224 offset:1024
	ds_read_b128 v[220:223], v224 offset:2048
	ds_read_b128 v[224:227], v224 offset:3072
	global_load_lds_dwordx4 v[228:229], off
	v_lshl_add_u64 v[228:229], v[230:231], 0, s[40:41]
	s_add_i32 m0, s22, 0x2000
	s_nop 0
	global_load_lds_dwordx4 v[228:229], off
	s_barrier
	s_waitcnt lgkmcnt(0)
	s_setprio 1
	s_waitcnt lgkmcnt(0)
	v_mfma_f32_16x16x32_bf16 v[116:119], v[212:215], v[176:179], v[116:119]
	v_mfma_f32_16x16x32_bf16 v[112:115], v[220:223], v[176:179], v[112:115]
	v_mfma_f32_16x16x32_bf16 v[100:103], v[212:215], v[184:187], v[100:103]
	v_mfma_f32_16x16x32_bf16 v[96:99], v[220:223], v[184:187], v[96:99]
	v_mfma_f32_16x16x32_bf16 v[84:87], v[212:215], v[192:195], v[84:87]
	v_mfma_f32_16x16x32_bf16 v[80:83], v[220:223], v[192:195], v[80:83]
	v_mfma_f32_16x16x32_bf16 v[68:71], v[212:215], v[204:207], v[68:71]
	v_mfma_f32_16x16x32_bf16 v[64:67], v[220:223], v[204:207], v[64:67]
	v_mfma_f32_16x16x32_bf16 v[116:119], v[216:219], v[180:183], v[116:119]
	v_mfma_f32_16x16x32_bf16 v[112:115], v[224:227], v[180:183], v[112:115]
	v_mfma_f32_16x16x32_bf16 v[100:103], v[216:219], v[188:191], v[100:103]
	v_mfma_f32_16x16x32_bf16 v[96:99], v[224:227], v[188:191], v[96:99]
	v_mfma_f32_16x16x32_bf16 v[84:87], v[216:219], v[200:203], v[84:87]
	v_mfma_f32_16x16x32_bf16 v[80:83], v[224:227], v[200:203], v[80:83]
	v_mfma_f32_16x16x32_bf16 v[68:71], v[216:219], v[208:211], v[68:71]
	v_mfma_f32_16x16x32_bf16 v[64:67], v[224:227], v[208:211], v[64:67]
	s_setprio 0
	s_mov_b32 m0, s79
	v_lshl_add_u64 v[228:229], v[232:233], 0, s[40:41]
	s_barrier
	ds_read_b128 v[176:179], v163 offset:49152
	ds_read_b128 v[180:183], v163 offset:50176
	ds_read_b128 v[184:187], v163 offset:51200
	ds_read_b128 v[188:191], v163 offset:52224
	ds_read_b128 v[192:195], v163 offset:53248
	ds_read_b128 v[200:203], v163 offset:54272
	ds_read_b128 v[204:207], v163 offset:55296
	ds_read_b128 v[208:211], v163 offset:56320
	global_load_lds_dwordx4 v[228:229], off
	v_lshl_add_u64 v[228:229], v[234:235], 0, s[40:41]
	s_mov_b32 m0, s80
	s_nop 0
	global_load_lds_dwordx4 v[228:229], off
	s_barrier
	s_waitcnt lgkmcnt(0)
	s_setprio 1
	s_waitcnt lgkmcnt(0)
	v_mfma_f32_16x16x32_bf16 v[60:63], v[144:147], v[176:179], v[60:63]
	v_mfma_f32_16x16x32_bf16 v[56:59], v[168:171], v[176:179], v[56:59]
	v_mfma_f32_16x16x32_bf16 v[44:47], v[144:147], v[184:187], v[44:47]
	v_mfma_f32_16x16x32_bf16 v[40:43], v[168:171], v[184:187], v[40:43]
	v_mfma_f32_16x16x32_bf16 v[28:31], v[144:147], v[192:195], v[28:31]
	v_mfma_f32_16x16x32_bf16 v[24:27], v[168:171], v[192:195], v[24:27]
	v_mfma_f32_16x16x32_bf16 v[12:15], v[144:147], v[204:207], v[12:15]
	v_mfma_f32_16x16x32_bf16 v[8:11], v[168:171], v[204:207], v[8:11]
	v_mfma_f32_16x16x32_bf16 v[60:63], v[164:167], v[180:183], v[60:63]
	v_mfma_f32_16x16x32_bf16 v[56:59], v[172:175], v[180:183], v[56:59]
	v_mfma_f32_16x16x32_bf16 v[44:47], v[164:167], v[188:191], v[44:47]
	v_mfma_f32_16x16x32_bf16 v[40:43], v[172:175], v[188:191], v[40:43]
	v_mfma_f32_16x16x32_bf16 v[28:31], v[164:167], v[200:203], v[28:31]
	v_mfma_f32_16x16x32_bf16 v[24:27], v[172:175], v[200:203], v[24:27]
	v_mfma_f32_16x16x32_bf16 v[12:15], v[164:167], v[208:211], v[12:15]
	v_mfma_f32_16x16x32_bf16 v[8:11], v[172:175], v[208:211], v[8:11]
	s_setprio 0
	s_barrier
	s_add_u32 s22, s50, 0x100080
	s_addc_u32 s23, s51, 0
	s_add_i32 s50, s52, s74
	v_lshl_add_u64 v[144:145], s[22:23], 0, v[138:139]
	s_mov_b32 m0, s50
	s_nop 0
	global_load_lds_dwordx4 v[144:145], off
	v_lshl_add_u64 v[144:145], s[22:23], 0, v[134:135]
	s_add_i32 m0, s50, 0x2000
	s_nop 0
	global_load_lds_dwordx4 v[144:145], off
	s_waitcnt vmcnt(6)
	s_barrier
	s_setprio 1
	v_mfma_f32_16x16x32_bf16 v[52:55], v[212:215], v[176:179], v[52:55]
	v_mfma_f32_16x16x32_bf16 v[48:51], v[220:223], v[176:179], v[48:51]
	v_mfma_f32_16x16x32_bf16 v[36:39], v[212:215], v[184:187], v[36:39]
	v_mfma_f32_16x16x32_bf16 v[32:35], v[220:223], v[184:187], v[32:35]
	v_mfma_f32_16x16x32_bf16 v[20:23], v[212:215], v[192:195], v[20:23]
	v_mfma_f32_16x16x32_bf16 v[16:19], v[220:223], v[192:195], v[16:19]
	v_mfma_f32_16x16x32_bf16 v[4:7], v[212:215], v[204:207], v[4:7]
	v_mfma_f32_16x16x32_bf16 v[0:3], v[220:223], v[204:207], v[0:3]
	v_mfma_f32_16x16x32_bf16 v[52:55], v[216:219], v[180:183], v[52:55]
	v_mfma_f32_16x16x32_bf16 v[48:51], v[224:227], v[180:183], v[48:51]
	v_mfma_f32_16x16x32_bf16 v[36:39], v[216:219], v[188:191], v[36:39]
	v_mfma_f32_16x16x32_bf16 v[32:35], v[224:227], v[188:191], v[32:35]
	v_mfma_f32_16x16x32_bf16 v[20:23], v[216:219], v[200:203], v[20:23]
	v_mfma_f32_16x16x32_bf16 v[16:19], v[224:227], v[200:203], v[16:19]
	v_mfma_f32_16x16x32_bf16 v[4:7], v[216:219], v[208:211], v[4:7]
	v_mfma_f32_16x16x32_bf16 v[0:3], v[224:227], v[208:211], v[0:3]
	s_setprio 0
	s_add_i32 s60, s60, 2
	s_add_u32 s48, s48, 0x100
	s_addc_u32 s49, s49, 0
	s_add_u32 s18, s18, 0x100
	s_addc_u32 s19, s19, 0
	s_cmp_gt_u32 s60, 61
	s_barrier
	s_cbranch_scc0 .LBB0_470
	v_add_u32_e32 v144, s33, v148
	v_ashrrev_i32_e32 v145, 31, v144
	v_readlane_b32 s18, v254, 56
	v_add_u32_e32 v146, s83, v150
	v_lshlrev_b64 v[164:165], 11, v[144:145]
	v_readlane_b32 s19, v254, 57
	v_ashrrev_i32_e32 v147, 31, v146
	s_nop 0
	v_lshl_add_u64 v[164:165], s[18:19], 0, v[164:165]
	v_lshl_add_u64 v[146:147], v[146:147], 1, v[164:165]
	global_load_dwordx4 v[164:167], v[146:147], off
	global_load_dwordx4 v[172:175], v[146:147], off offset:256
	s_mov_b64 s[98:99], 0x8000
	v_lshl_add_u64 v[236:237], v[146:147], 0, s[98:99]
	global_load_dwordx4 v[176:179], v[236:237], off
	s_mov_b64 s[98:99], 0x8000
	v_lshl_add_u64 v[236:237], v[146:147], 0, s[98:99]
	global_load_dwordx4 v[180:183], v[236:237], off offset:256
	s_mov_b64 s[98:99], 0x10000
	v_lshl_add_u64 v[236:237], v[146:147], 0, s[98:99]
	global_load_dwordx4 v[184:187], v[236:237], off
	s_mov_b64 s[98:99], 0x10000
	v_lshl_add_u64 v[236:237], v[146:147], 0, s[98:99]
	global_load_dwordx4 v[188:191], v[236:237], off offset:256
	s_mov_b64 s[98:99], 0x18000
	v_lshl_add_u64 v[236:237], v[146:147], 0, s[98:99]
	global_load_dwordx4 v[192:195], v[236:237], off
	s_mov_b64 s[98:99], 0x18000
	v_lshl_add_u64 v[236:237], v[146:147], 0, s[98:99]
	global_load_dwordx4 v[200:203], v[236:237], off offset:256
	s_mov_b64 s[98:99], 0x40000
	v_lshl_add_u64 v[236:237], v[146:147], 0, s[98:99]
	global_load_dwordx4 v[204:207], v[236:237], off
	s_mov_b64 s[98:99], 0x40000
	v_lshl_add_u64 v[236:237], v[146:147], 0, s[98:99]
	global_load_dwordx4 v[208:211], v[236:237], off offset:256
	s_mov_b64 s[98:99], 0x48000
	v_lshl_add_u64 v[236:237], v[146:147], 0, s[98:99]
	global_load_dwordx4 v[212:215], v[236:237], off
	s_mov_b64 s[98:99], 0x48000
	v_lshl_add_u64 v[236:237], v[146:147], 0, s[98:99]
	global_load_dwordx4 v[216:219], v[236:237], off offset:256
	s_mov_b64 s[98:99], 0x50000
	v_lshl_add_u64 v[236:237], v[146:147], 0, s[98:99]
	global_load_dwordx4 v[220:223], v[236:237], off
	s_mov_b64 s[98:99], 0x50000
	v_lshl_add_u64 v[236:237], v[146:147], 0, s[98:99]
	global_load_dwordx4 v[224:227], v[236:237], off offset:256
	s_mov_b64 s[98:99], 0x58000
	v_lshl_add_u64 v[236:237], v[146:147], 0, s[98:99]
	global_load_dwordx4 v[228:231], v[236:237], off
	s_mov_b64 s[98:99], 0x58000
	v_lshl_add_u64 v[236:237], v[146:147], 0, s[98:99]
	global_load_dwordx4 v[232:235], v[236:237], off offset:256
	s_mov_b64 s[18:19], 0x8000
	s_waitcnt vmcnt(15)
	v_lshlrev_b32_e32 v168, 16, v164
	v_and_b32_e32 v169, 0xffff0000, v164
	v_lshlrev_b32_e32 v164, 16, v165
	v_and_b32_e32 v165, 0xffff0000, v165
	v_lshlrev_b32_e32 v170, 16, v166
	v_and_b32_e32 v171, 0xffff0000, v166
	v_lshlrev_b32_e32 v166, 16, v167
	v_and_b32_e32 v167, 0xffff0000, v167
	v_pk_add_f32 v[126:127], v[126:127], v[164:165]
	v_pk_add_f32 v[124:125], v[124:125], v[168:169]
	v_pk_add_f32 v[164:165], v[122:123], v[166:167]
	v_pk_add_f32 v[166:167], v[120:121], v[170:171]
	v_cvt_pk_bf16_f32 v120, v124, v125
	v_cvt_pk_bf16_f32 v121, v126, v127
	v_cvt_pk_bf16_f32 v123, v164, v165
	v_mul_f32_e32 v168, v125, v125
	v_cvt_pk_bf16_f32 v122, v166, v167
	global_store_dwordx4 v[146:147], v[120:123], off
	v_fmac_f32_e32 v168, v124, v124
	v_fmac_f32_e32 v168, v126, v126
	v_fmac_f32_e32 v168, v127, v127
	v_fmac_f32_e32 v168, v166, v166
	v_fmac_f32_e32 v168, v167, v167
	v_fmac_f32_e32 v168, v164, v164
	v_fmac_f32_e32 v168, v165, v165
	s_waitcnt vmcnt(15)
	s_nop 1
	v_mov_b32_e32 v120, v172
	v_mov_b32_e32 v121, v173
	v_mov_b32_e32 v122, v174
	v_mov_b32_e32 v123, v175
	v_lshlrev_b32_e32 v124, 16, v120
	v_and_b32_e32 v125, 0xffff0000, v120
	v_lshlrev_b32_e32 v120, 16, v121
	v_and_b32_e32 v121, 0xffff0000, v121
	v_lshlrev_b32_e32 v126, 16, v122
	v_and_b32_e32 v127, 0xffff0000, v122
	v_lshlrev_b32_e32 v122, 16, v123
	v_and_b32_e32 v123, 0xffff0000, v123
	v_pk_add_f32 v[118:119], v[118:119], v[120:121]
	v_pk_add_f32 v[116:117], v[116:117], v[124:125]
	v_pk_add_f32 v[120:121], v[114:115], v[122:123]
	v_pk_add_f32 v[122:123], v[112:113], v[126:127]
	v_cvt_pk_bf16_f32 v112, v116, v117
	v_cvt_pk_bf16_f32 v113, v118, v119
	v_cvt_pk_bf16_f32 v115, v120, v121
	s_nop 0
	v_cvt_pk_bf16_f32 v114, v122, v123
	global_store_dwordx4 v[146:147], v[112:115], off offset:256
	s_nop 1
	v_mul_f32_e32 v112, v117, v117
	v_fmac_f32_e32 v112, v116, v116
	v_fmac_f32_e32 v112, v118, v118
	v_fmac_f32_e32 v112, v119, v119
	v_fmac_f32_e32 v112, v122, v122
	v_fmac_f32_e32 v112, v123, v123
	v_lshl_add_u64 v[118:119], v[146:147], 0, s[18:19]
	s_mov_b32 s18, 0x8000
	v_fmac_f32_e32 v112, v120, v120
	v_add_co_u32_e32 v120, vcc, s18, v146
	v_fmac_f32_e32 v112, v121, v121
	s_nop 0
	v_addc_co_u32_e32 v121, vcc, 0, v147, vcc
	s_mov_b64 s[18:19], 0x10000
	v_add_f32_e32 v112, v168, v112
	s_waitcnt vmcnt(15)
	s_nop 1
	v_mov_b32_e32 v114, v176
	v_mov_b32_e32 v115, v177
	v_mov_b32_e32 v116, v178
	v_mov_b32_e32 v117, v179
	v_lshlrev_b32_e32 v122, 16, v114
	v_and_b32_e32 v123, 0xffff0000, v114
	v_lshlrev_b32_e32 v114, 16, v115
	v_and_b32_e32 v115, 0xffff0000, v115
	v_lshlrev_b32_e32 v124, 16, v116
	v_and_b32_e32 v125, 0xffff0000, v116
	v_lshlrev_b32_e32 v116, 16, v117
	v_and_b32_e32 v117, 0xffff0000, v117
	v_pk_add_f32 v[110:111], v[110:111], v[114:115]
	v_pk_add_f32 v[108:109], v[108:109], v[122:123]
	v_pk_add_f32 v[114:115], v[106:107], v[116:117]
	v_pk_add_f32 v[116:117], v[104:105], v[124:125]
	v_cvt_pk_bf16_f32 v104, v108, v109
	v_cvt_pk_bf16_f32 v105, v110, v111
	v_cvt_pk_bf16_f32 v107, v114, v115
	v_mul_f32_e32 v113, v109, v109
	v_cvt_pk_bf16_f32 v106, v116, v117
	global_store_dwordx4 v[120:121], v[104:107], off
	v_fmac_f32_e32 v113, v108, v108
	v_fmac_f32_e32 v113, v110, v110
	v_fmac_f32_e32 v113, v111, v111
	v_fmac_f32_e32 v113, v116, v116
	v_fmac_f32_e32 v113, v117, v117
	v_fmac_f32_e32 v113, v114, v114
	v_fmac_f32_e32 v113, v115, v115
	s_waitcnt vmcnt(15)
	s_nop 1
	v_mov_b32_e32 v104, v180
	v_mov_b32_e32 v105, v181
	v_mov_b32_e32 v106, v182
	v_mov_b32_e32 v107, v183
	v_lshlrev_b32_e32 v108, 16, v104
	v_and_b32_e32 v109, 0xffff0000, v104
	v_lshlrev_b32_e32 v104, 16, v105
	v_and_b32_e32 v105, 0xffff0000, v105
	v_lshlrev_b32_e32 v110, 16, v106
	v_and_b32_e32 v111, 0xffff0000, v106
	v_lshlrev_b32_e32 v106, 16, v107
	v_and_b32_e32 v107, 0xffff0000, v107
	v_pk_add_f32 v[102:103], v[102:103], v[104:105]
	v_pk_add_f32 v[100:101], v[100:101], v[108:109]
	v_pk_add_f32 v[104:105], v[98:99], v[106:107]
	v_pk_add_f32 v[106:107], v[96:97], v[110:111]
	v_cvt_pk_bf16_f32 v96, v100, v101
	v_cvt_pk_bf16_f32 v97, v102, v103
	v_cvt_pk_bf16_f32 v99, v104, v105
	s_nop 0
	v_cvt_pk_bf16_f32 v98, v106, v107
	global_store_dwordx4 v[118:119], v[96:99], off offset:256
	s_nop 1
	v_mul_f32_e32 v96, v101, v101
	v_fmac_f32_e32 v96, v100, v100
	v_fmac_f32_e32 v96, v102, v102
	v_fmac_f32_e32 v96, v103, v103
	v_fmac_f32_e32 v96, v106, v106
	v_fmac_f32_e32 v96, v107, v107
	v_fmac_f32_e32 v96, v104, v104
	v_fmac_f32_e32 v96, v105, v105
	v_add_f32_e32 v98, v113, v96
	v_lshl_add_u64 v[96:97], v[146:147], 0, s[18:19]
	s_mov_b32 s18, 0x10000
	v_add_co_u32_e32 v104, vcc, s18, v146
	s_mov_b64 s[18:19], 0x18000
	s_nop 0
	v_addc_co_u32_e32 v105, vcc, 0, v147, vcc
	s_waitcnt vmcnt(15)
	s_nop 1
	v_mov_b32_e32 v100, v184
	v_mov_b32_e32 v101, v185
	v_mov_b32_e32 v102, v186
	v_mov_b32_e32 v103, v187
	v_lshlrev_b32_e32 v106, 16, v100
	v_and_b32_e32 v107, 0xffff0000, v100
	v_lshlrev_b32_e32 v100, 16, v101
	v_and_b32_e32 v101, 0xffff0000, v101
	v_lshlrev_b32_e32 v108, 16, v102
	v_and_b32_e32 v109, 0xffff0000, v102
	v_lshlrev_b32_e32 v102, 16, v103
	v_and_b32_e32 v103, 0xffff0000, v103
	v_pk_add_f32 v[94:95], v[94:95], v[100:101]
	v_pk_add_f32 v[92:93], v[92:93], v[106:107]
	v_pk_add_f32 v[100:101], v[90:91], v[102:103]
	v_pk_add_f32 v[102:103], v[88:89], v[108:109]
	v_cvt_pk_bf16_f32 v88, v92, v93
	v_cvt_pk_bf16_f32 v89, v94, v95
	v_cvt_pk_bf16_f32 v91, v100, v101
	v_mul_f32_e32 v99, v93, v93
	v_cvt_pk_bf16_f32 v90, v102, v103
	global_store_dwordx4 v[104:105], v[88:91], off
	v_fmac_f32_e32 v99, v92, v92
	v_fmac_f32_e32 v99, v94, v94
	v_fmac_f32_e32 v99, v95, v95
	v_fmac_f32_e32 v99, v102, v102
	v_fmac_f32_e32 v99, v103, v103
	v_fmac_f32_e32 v99, v100, v100
	v_fmac_f32_e32 v99, v101, v101
	s_waitcnt vmcnt(15)
	s_nop 1
	v_mov_b32_e32 v88, v188
	v_mov_b32_e32 v89, v189
	v_mov_b32_e32 v90, v190
	v_mov_b32_e32 v91, v191
	v_lshlrev_b32_e32 v92, 16, v88
	v_and_b32_e32 v93, 0xffff0000, v88
	v_lshlrev_b32_e32 v88, 16, v89
	v_and_b32_e32 v89, 0xffff0000, v89
	v_lshlrev_b32_e32 v94, 16, v90
	v_and_b32_e32 v95, 0xffff0000, v90
	v_lshlrev_b32_e32 v90, 16, v91
	v_and_b32_e32 v91, 0xffff0000, v91
	v_pk_add_f32 v[86:87], v[86:87], v[88:89]
	v_pk_add_f32 v[84:85], v[84:85], v[92:93]
	v_pk_add_f32 v[88:89], v[82:83], v[90:91]
	v_pk_add_f32 v[90:91], v[80:81], v[94:95]
	v_cvt_pk_bf16_f32 v80, v84, v85
	v_cvt_pk_bf16_f32 v81, v86, v87
	v_cvt_pk_bf16_f32 v83, v88, v89
	s_nop 0
	v_cvt_pk_bf16_f32 v82, v90, v91
	global_store_dwordx4 v[96:97], v[80:83], off offset:256
	s_nop 1
	v_mul_f32_e32 v80, v85, v85
	v_fmac_f32_e32 v80, v84, v84
	v_fmac_f32_e32 v80, v86, v86
	v_fmac_f32_e32 v80, v87, v87
	v_fmac_f32_e32 v80, v90, v90
	v_fmac_f32_e32 v80, v91, v91
	v_fmac_f32_e32 v80, v88, v88
	v_fmac_f32_e32 v80, v89, v89
	v_add_f32_e32 v82, v99, v80
	v_lshl_add_u64 v[80:81], v[146:147], 0, s[18:19]
	s_mov_b32 s18, 0x18000
	v_add_co_u32_e32 v88, vcc, s18, v146
	s_mov_b64 s[18:19], 0x40000
	s_nop 0
	v_addc_co_u32_e32 v89, vcc, 0, v147, vcc
	s_waitcnt vmcnt(15)
	s_nop 1
	v_mov_b32_e32 v84, v192
	v_mov_b32_e32 v85, v193
	v_mov_b32_e32 v86, v194
	v_mov_b32_e32 v87, v195
	v_lshlrev_b32_e32 v90, 16, v84
	v_and_b32_e32 v91, 0xffff0000, v84
	v_lshlrev_b32_e32 v84, 16, v85
	v_and_b32_e32 v85, 0xffff0000, v85
	v_lshlrev_b32_e32 v92, 16, v86
	v_and_b32_e32 v93, 0xffff0000, v86
	v_lshlrev_b32_e32 v86, 16, v87
	v_and_b32_e32 v87, 0xffff0000, v87
	v_pk_add_f32 v[78:79], v[78:79], v[84:85]
	v_pk_add_f32 v[76:77], v[76:77], v[90:91]
	v_pk_add_f32 v[84:85], v[74:75], v[86:87]
	v_pk_add_f32 v[86:87], v[72:73], v[92:93]
	v_cvt_pk_bf16_f32 v72, v76, v77
	v_cvt_pk_bf16_f32 v73, v78, v79
	v_cvt_pk_bf16_f32 v75, v84, v85
	v_mul_f32_e32 v83, v77, v77
	v_cvt_pk_bf16_f32 v74, v86, v87
	global_store_dwordx4 v[88:89], v[72:75], off
	v_fmac_f32_e32 v83, v76, v76
	v_fmac_f32_e32 v83, v78, v78
	v_fmac_f32_e32 v83, v79, v79
	v_fmac_f32_e32 v83, v86, v86
	v_fmac_f32_e32 v83, v87, v87
	v_fmac_f32_e32 v83, v84, v84
	v_fmac_f32_e32 v83, v85, v85
	s_waitcnt vmcnt(15)
	s_nop 1
	v_mov_b32_e32 v72, v200
	v_mov_b32_e32 v73, v201
	v_mov_b32_e32 v74, v202
	v_mov_b32_e32 v75, v203
	v_lshlrev_b32_e32 v76, 16, v72
	v_and_b32_e32 v77, 0xffff0000, v72
	v_lshlrev_b32_e32 v72, 16, v73
	v_and_b32_e32 v73, 0xffff0000, v73
	v_lshlrev_b32_e32 v78, 16, v74
	v_and_b32_e32 v79, 0xffff0000, v74
	v_lshlrev_b32_e32 v74, 16, v75
	v_and_b32_e32 v75, 0xffff0000, v75
	v_pk_add_f32 v[70:71], v[70:71], v[72:73]
	v_pk_add_f32 v[68:69], v[68:69], v[76:77]
	v_pk_add_f32 v[72:73], v[66:67], v[74:75]
	v_pk_add_f32 v[74:75], v[64:65], v[78:79]
	v_cvt_pk_bf16_f32 v64, v68, v69
	v_cvt_pk_bf16_f32 v65, v70, v71
	v_cvt_pk_bf16_f32 v67, v72, v73
	s_nop 0
	v_cvt_pk_bf16_f32 v66, v74, v75
	global_store_dwordx4 v[80:81], v[64:67], off offset:256
	s_nop 1
	v_mul_f32_e32 v64, v69, v69
	v_fmac_f32_e32 v64, v68, v68
	v_fmac_f32_e32 v64, v70, v70
	v_fmac_f32_e32 v64, v71, v71
	v_fmac_f32_e32 v64, v74, v74
	v_fmac_f32_e32 v64, v75, v75
	v_fmac_f32_e32 v64, v72, v72
	v_fmac_f32_e32 v64, v73, v73
	v_add_f32_e32 v66, v83, v64
	v_lshl_add_u64 v[64:65], v[146:147], 0, s[18:19]
	s_mov_b32 s18, 0x40000
	v_add_co_u32_e32 v72, vcc, s18, v146
	s_mov_b64 s[18:19], 0x48000
	s_nop 0
	v_addc_co_u32_e32 v73, vcc, 0, v147, vcc
	s_waitcnt vmcnt(15)
	s_nop 1
	v_mov_b32_e32 v68, v204
	v_mov_b32_e32 v69, v205
	v_mov_b32_e32 v70, v206
	v_mov_b32_e32 v71, v207
	v_lshlrev_b32_e32 v74, 16, v68
	v_and_b32_e32 v75, 0xffff0000, v68
	v_lshlrev_b32_e32 v68, 16, v69
	v_and_b32_e32 v69, 0xffff0000, v69
	v_lshlrev_b32_e32 v76, 16, v70
	v_and_b32_e32 v77, 0xffff0000, v70
	v_lshlrev_b32_e32 v70, 16, v71
	v_and_b32_e32 v71, 0xffff0000, v71
	v_pk_add_f32 v[62:63], v[62:63], v[68:69]
	v_pk_add_f32 v[60:61], v[60:61], v[74:75]
	v_pk_add_f32 v[68:69], v[58:59], v[70:71]
	v_pk_add_f32 v[70:71], v[56:57], v[76:77]
	v_cvt_pk_bf16_f32 v56, v60, v61
	v_cvt_pk_bf16_f32 v57, v62, v63
	v_cvt_pk_bf16_f32 v59, v68, v69
	v_mul_f32_e32 v67, v61, v61
	v_cvt_pk_bf16_f32 v58, v70, v71
	global_store_dwordx4 v[72:73], v[56:59], off
	v_fmac_f32_e32 v67, v60, v60
	v_fmac_f32_e32 v67, v62, v62
	v_fmac_f32_e32 v67, v63, v63
	v_fmac_f32_e32 v67, v70, v70
	v_fmac_f32_e32 v67, v71, v71
	v_fmac_f32_e32 v67, v68, v68
	v_fmac_f32_e32 v67, v69, v69
	s_waitcnt vmcnt(15)
	s_nop 1
	v_mov_b32_e32 v56, v208
	v_mov_b32_e32 v57, v209
	v_mov_b32_e32 v58, v210
	v_mov_b32_e32 v59, v211
	v_lshlrev_b32_e32 v60, 16, v56
	v_and_b32_e32 v61, 0xffff0000, v56
	v_lshlrev_b32_e32 v56, 16, v57
	v_and_b32_e32 v57, 0xffff0000, v57
	v_lshlrev_b32_e32 v62, 16, v58
	v_and_b32_e32 v63, 0xffff0000, v58
	v_lshlrev_b32_e32 v58, 16, v59
	v_and_b32_e32 v59, 0xffff0000, v59
	v_pk_add_f32 v[54:55], v[54:55], v[56:57]
	v_pk_add_f32 v[52:53], v[52:53], v[60:61]
	v_pk_add_f32 v[56:57], v[50:51], v[58:59]
	v_pk_add_f32 v[58:59], v[48:49], v[62:63]
	v_cvt_pk_bf16_f32 v48, v52, v53
	v_cvt_pk_bf16_f32 v49, v54, v55
	v_cvt_pk_bf16_f32 v51, v56, v57
	s_nop 0
	v_cvt_pk_bf16_f32 v50, v58, v59
	global_store_dwordx4 v[64:65], v[48:51], off offset:256
	s_nop 1
	v_mul_f32_e32 v48, v53, v53
	v_fmac_f32_e32 v48, v52, v52
	v_fmac_f32_e32 v48, v54, v54
	v_fmac_f32_e32 v48, v55, v55
	v_fmac_f32_e32 v48, v58, v58
	v_fmac_f32_e32 v48, v59, v59
	v_fmac_f32_e32 v48, v56, v56
	v_fmac_f32_e32 v48, v57, v57
	v_add_f32_e32 v50, v67, v48
	v_lshl_add_u64 v[48:49], v[146:147], 0, s[18:19]
	s_mov_b32 s18, 0x48000
	v_add_co_u32_e32 v56, vcc, s18, v146
	s_mov_b64 s[18:19], 0x50000
	s_nop 0
	v_addc_co_u32_e32 v57, vcc, 0, v147, vcc
	s_waitcnt vmcnt(15)
	s_nop 1
	v_mov_b32_e32 v52, v212
	v_mov_b32_e32 v53, v213
	v_mov_b32_e32 v54, v214
	v_mov_b32_e32 v55, v215
	v_lshlrev_b32_e32 v58, 16, v52
	v_and_b32_e32 v59, 0xffff0000, v52
	v_lshlrev_b32_e32 v52, 16, v53
	v_and_b32_e32 v53, 0xffff0000, v53
	v_lshlrev_b32_e32 v60, 16, v54
	v_and_b32_e32 v61, 0xffff0000, v54
	v_lshlrev_b32_e32 v54, 16, v55
	v_and_b32_e32 v55, 0xffff0000, v55
	v_pk_add_f32 v[46:47], v[46:47], v[52:53]
	v_pk_add_f32 v[44:45], v[44:45], v[58:59]
	v_pk_add_f32 v[52:53], v[42:43], v[54:55]
	v_pk_add_f32 v[54:55], v[40:41], v[60:61]
	v_cvt_pk_bf16_f32 v40, v44, v45
	v_cvt_pk_bf16_f32 v41, v46, v47
	v_cvt_pk_bf16_f32 v43, v52, v53
	v_mul_f32_e32 v51, v45, v45
	v_cvt_pk_bf16_f32 v42, v54, v55
	global_store_dwordx4 v[56:57], v[40:43], off
	v_fmac_f32_e32 v51, v44, v44
	v_fmac_f32_e32 v51, v46, v46
	v_fmac_f32_e32 v51, v47, v47
	v_fmac_f32_e32 v51, v54, v54
	v_fmac_f32_e32 v51, v55, v55
	v_fmac_f32_e32 v51, v52, v52
	v_fmac_f32_e32 v51, v53, v53
	s_waitcnt vmcnt(15)
	s_nop 1
	v_mov_b32_e32 v40, v216
	v_mov_b32_e32 v41, v217
	v_mov_b32_e32 v42, v218
	v_mov_b32_e32 v43, v219
	v_lshlrev_b32_e32 v44, 16, v40
	v_and_b32_e32 v45, 0xffff0000, v40
	v_lshlrev_b32_e32 v40, 16, v41
	v_and_b32_e32 v41, 0xffff0000, v41
	v_lshlrev_b32_e32 v46, 16, v42
	v_and_b32_e32 v47, 0xffff0000, v42
	v_lshlrev_b32_e32 v42, 16, v43
	v_and_b32_e32 v43, 0xffff0000, v43
	v_pk_add_f32 v[38:39], v[38:39], v[40:41]
	v_pk_add_f32 v[36:37], v[36:37], v[44:45]
	v_pk_add_f32 v[40:41], v[34:35], v[42:43]
	v_pk_add_f32 v[42:43], v[32:33], v[46:47]
	v_cvt_pk_bf16_f32 v32, v36, v37
	v_cvt_pk_bf16_f32 v33, v38, v39
	v_cvt_pk_bf16_f32 v35, v40, v41
	s_nop 0
	v_cvt_pk_bf16_f32 v34, v42, v43
	global_store_dwordx4 v[48:49], v[32:35], off offset:256
	s_nop 1
	v_mul_f32_e32 v32, v37, v37
	v_fmac_f32_e32 v32, v36, v36
	v_fmac_f32_e32 v32, v38, v38
	v_fmac_f32_e32 v32, v39, v39
	v_fmac_f32_e32 v32, v42, v42
	v_fmac_f32_e32 v32, v43, v43
	v_fmac_f32_e32 v32, v40, v40
	v_fmac_f32_e32 v32, v41, v41
	v_add_f32_e32 v34, v51, v32
	v_lshl_add_u64 v[32:33], v[146:147], 0, s[18:19]
	s_mov_b32 s18, 0x50000
	v_add_co_u32_e32 v40, vcc, s18, v146
	s_mov_b64 s[18:19], 0x58000
	s_nop 0
	v_addc_co_u32_e32 v41, vcc, 0, v147, vcc
	s_waitcnt vmcnt(15)
	s_nop 1
	v_mov_b32_e32 v36, v220
	v_mov_b32_e32 v37, v221
	v_mov_b32_e32 v38, v222
	v_mov_b32_e32 v39, v223
	v_lshlrev_b32_e32 v42, 16, v36
	v_and_b32_e32 v43, 0xffff0000, v36
	v_lshlrev_b32_e32 v36, 16, v37
	v_and_b32_e32 v37, 0xffff0000, v37
	v_lshlrev_b32_e32 v44, 16, v38
	v_and_b32_e32 v45, 0xffff0000, v38
	v_lshlrev_b32_e32 v38, 16, v39
	v_and_b32_e32 v39, 0xffff0000, v39
	v_pk_add_f32 v[30:31], v[30:31], v[36:37]
	v_pk_add_f32 v[28:29], v[28:29], v[42:43]
	v_pk_add_f32 v[36:37], v[26:27], v[38:39]
	v_pk_add_f32 v[38:39], v[24:25], v[44:45]
	v_cvt_pk_bf16_f32 v24, v28, v29
	v_cvt_pk_bf16_f32 v25, v30, v31
	v_cvt_pk_bf16_f32 v27, v36, v37
	v_mul_f32_e32 v35, v29, v29
	v_cvt_pk_bf16_f32 v26, v38, v39
	global_store_dwordx4 v[40:41], v[24:27], off
	v_fmac_f32_e32 v35, v28, v28
	v_fmac_f32_e32 v35, v30, v30
	v_fmac_f32_e32 v35, v31, v31
	v_fmac_f32_e32 v35, v38, v38
	v_fmac_f32_e32 v35, v39, v39
	v_fmac_f32_e32 v35, v36, v36
	v_fmac_f32_e32 v35, v37, v37
	s_waitcnt vmcnt(15)
	s_nop 1
	v_mov_b32_e32 v24, v224
	v_mov_b32_e32 v25, v225
	v_mov_b32_e32 v26, v226
	v_mov_b32_e32 v27, v227
	v_lshlrev_b32_e32 v28, 16, v24
	v_and_b32_e32 v29, 0xffff0000, v24
	v_lshlrev_b32_e32 v24, 16, v25
	v_and_b32_e32 v25, 0xffff0000, v25
	v_lshlrev_b32_e32 v30, 16, v26
	v_and_b32_e32 v31, 0xffff0000, v26
	v_lshlrev_b32_e32 v26, 16, v27
	v_and_b32_e32 v27, 0xffff0000, v27
	v_pk_add_f32 v[22:23], v[22:23], v[24:25]
	v_pk_add_f32 v[20:21], v[20:21], v[28:29]
	v_pk_add_f32 v[24:25], v[18:19], v[26:27]
	v_pk_add_f32 v[26:27], v[16:17], v[30:31]
	v_cvt_pk_bf16_f32 v16, v20, v21
	v_cvt_pk_bf16_f32 v17, v22, v23
	v_cvt_pk_bf16_f32 v19, v24, v25
	s_nop 0
	v_cvt_pk_bf16_f32 v18, v26, v27
	global_store_dwordx4 v[32:33], v[16:19], off offset:256
	s_nop 1
	v_mul_f32_e32 v16, v21, v21
	v_fmac_f32_e32 v16, v20, v20
	v_fmac_f32_e32 v16, v22, v22
	v_fmac_f32_e32 v16, v23, v23
	v_fmac_f32_e32 v16, v26, v26
	v_fmac_f32_e32 v16, v27, v27
	v_fmac_f32_e32 v16, v24, v24
	v_fmac_f32_e32 v16, v25, v25
	v_add_f32_e32 v18, v35, v16
	v_lshl_add_u64 v[16:17], v[146:147], 0, s[18:19]
	s_mov_b32 s18, 0x58000
	v_add_co_u32_e32 v24, vcc, s18, v146
	s_nop 1
	v_addc_co_u32_e32 v25, vcc, 0, v147, vcc
	s_waitcnt vmcnt(15)
	s_nop 1
	v_mov_b32_e32 v20, v228
	v_mov_b32_e32 v21, v229
	v_mov_b32_e32 v22, v230
	v_mov_b32_e32 v23, v231
	v_lshlrev_b32_e32 v26, 16, v20
	v_and_b32_e32 v27, 0xffff0000, v20
	v_lshlrev_b32_e32 v20, 16, v21
	v_and_b32_e32 v21, 0xffff0000, v21
	v_lshlrev_b32_e32 v28, 16, v22
	v_and_b32_e32 v29, 0xffff0000, v22
	v_lshlrev_b32_e32 v22, 16, v23
	v_and_b32_e32 v23, 0xffff0000, v23
	v_pk_add_f32 v[14:15], v[14:15], v[20:21]
	v_pk_add_f32 v[20:21], v[12:13], v[26:27]
	v_pk_add_f32 v[22:23], v[10:11], v[22:23]
	v_pk_add_f32 v[26:27], v[8:9], v[28:29]
	v_cvt_pk_bf16_f32 v8, v20, v21
	v_cvt_pk_bf16_f32 v9, v14, v15
	v_cvt_pk_bf16_f32 v11, v22, v23
	v_mul_f32_e32 v12, v21, v21
	v_cvt_pk_bf16_f32 v10, v26, v27
	global_store_dwordx4 v[24:25], v[8:11], off
	v_fmac_f32_e32 v12, v20, v20
	v_fmac_f32_e32 v12, v14, v14
	v_fmac_f32_e32 v12, v15, v15
	v_fmac_f32_e32 v12, v26, v26
	v_fmac_f32_e32 v12, v27, v27
	v_fmac_f32_e32 v12, v22, v22
	v_fmac_f32_e32 v12, v23, v23
	s_waitcnt vmcnt(15)
	s_nop 1
	v_mov_b32_e32 v8, v232
	v_mov_b32_e32 v9, v233
	v_mov_b32_e32 v10, v234
	v_mov_b32_e32 v11, v235
	v_lshlrev_b32_e32 v14, 16, v8
	v_and_b32_e32 v15, 0xffff0000, v8
	v_lshlrev_b32_e32 v8, 16, v9
	v_and_b32_e32 v9, 0xffff0000, v9
	v_lshlrev_b32_e32 v20, 16, v10
	v_and_b32_e32 v21, 0xffff0000, v10
	v_lshlrev_b32_e32 v10, 16, v11
	v_and_b32_e32 v11, 0xffff0000, v11
	v_pk_add_f32 v[6:7], v[6:7], v[8:9]
	v_pk_add_f32 v[4:5], v[4:5], v[14:15]
	v_pk_add_f32 v[8:9], v[2:3], v[10:11]
	v_pk_add_f32 v[10:11], v[0:1], v[20:21]
	v_cvt_pk_bf16_f32 v0, v4, v5
	v_cvt_pk_bf16_f32 v1, v6, v7
	v_cvt_pk_bf16_f32 v3, v8, v9
	s_nop 0
	v_cvt_pk_bf16_f32 v2, v10, v11
	global_store_dwordx4 v[16:17], v[0:3], off offset:256
	ds_bpermute_b32 v2, v151, v98
	s_nop 0
	v_mul_f32_e32 v0, v5, v5
	v_fmac_f32_e32 v0, v4, v4
	v_fmac_f32_e32 v0, v6, v6
	v_fmac_f32_e32 v0, v7, v7
	v_fmac_f32_e32 v0, v10, v10
	v_fmac_f32_e32 v0, v11, v11
	v_fmac_f32_e32 v0, v8, v8
	v_fmac_f32_e32 v0, v9, v9
	v_add_f32_e32 v14, v12, v0
	ds_bpermute_b32 v0, v151, v112
	ds_bpermute_b32 v4, v151, v82
	ds_bpermute_b32 v6, v151, v66
	ds_bpermute_b32 v8, v151, v50
	ds_bpermute_b32 v10, v151, v34
	ds_bpermute_b32 v12, v151, v18
	ds_bpermute_b32 v15, v151, v14
	s_waitcnt lgkmcnt(0)
	v_add_f32_e32 v0, v112, v0
	v_add_f32_e32 v2, v98, v2
	v_add_f32_e32 v4, v82, v4
	v_add_f32_e32 v6, v66, v6
	v_add_f32_e32 v8, v50, v8
	v_add_f32_e32 v10, v34, v10
	v_add_f32_e32 v12, v18, v12
	v_add_f32_e32 v14, v14, v15
	ds_bpermute_b32 v1, v152, v0
	ds_bpermute_b32 v3, v152, v2
	ds_bpermute_b32 v5, v152, v4
	ds_bpermute_b32 v7, v152, v6
	ds_bpermute_b32 v9, v152, v8
	ds_bpermute_b32 v11, v152, v10
	ds_bpermute_b32 v13, v152, v12
	ds_bpermute_b32 v15, v152, v14
	s_and_saveexec_b64 s[48:49], s[2:3]
	s_cbranch_execz .LBB0_473
	s_waitcnt lgkmcnt(6)
	v_add_f32_e32 v2, v2, v3
	v_add_f32_e32 v0, v0, v1
	v_add_u32_e32 v1, s82, v153
	s_waitcnt lgkmcnt(2)
	v_add_f32_e32 v10, v10, v11
	v_add_f32_e32 v8, v8, v9
	v_add_f32_e32 v6, v6, v7
	v_add_f32_e32 v4, v4, v5
	ds_write2st64_b32 v1, v0, v2 offset1:1
	ds_write2st64_b32 v1, v4, v6 offset0:2 offset1:3
	v_add_u32_e32 v0, s82, v157
	s_waitcnt lgkmcnt(2)
	v_add_f32_e32 v14, v14, v15
	v_add_f32_e32 v12, v12, v13
	ds_write2st64_b32 v0, v8, v10 offset1:1
	ds_write2st64_b32 v0, v12, v14 offset0:2 offset1:3
